# stack1 + removed back-to-back s_setprio 0/1 pairs between adjacent MFMA blocks in GEMM K-loops
# speedup vs baseline: 1.0039x; 1.0039x over previous
.LBB0_194:
	s_add_u32 s24, s22, 0xfffc0080
	s_addc_u32 s25, s23, -1
	s_add_i32 s55, 0, 0x10000
	s_cmp_eq_u32 s54, 12
	s_cselect_b32 s27, s15, s25
	s_cselect_b32 s26, s46, s24
	v_add_u32_e32 v140, s55, v143
	s_cselect_b32 s25, s13, s53
	s_cselect_b32 s24, s47, s52
	s_add_i32 s69, 0, 0x14000
	ds_read_b128 v[162:165], v140
	ds_read_b128 v[166:169], v140 offset:1024
	ds_read_b128 v[170:173], v140 offset:2048
	ds_read_b128 v[174:177], v140 offset:3072
	v_add_u32_e32 v140, s69, v143
	ds_read_b128 v[178:181], v140
	ds_read_b128 v[182:185], v140 offset:1024
	ds_read_b128 v[186:189], v140 offset:2048
	ds_read_b128 v[190:193], v140 offset:3072
	v_lshl_add_u64 v[140:141], s[22:23], 0, v[136:137]
	s_add_i32 m0, s38, 0xc000
	ds_read_b128 v[194:197], v145
	ds_read_b128 v[198:201], v145 offset:1024
	ds_read_b128 v[202:205], v145 offset:2048
	ds_read_b128 v[206:209], v145 offset:3072
	ds_read_b128 v[232:235], v145 offset:4096
	ds_read_b128 v[236:239], v145 offset:5120
	ds_read_b128 v[240:243], v145 offset:6144
	ds_read_b128 v[244:247], v145 offset:7168
	global_load_lds_dwordx4 v[140:141], off
	v_lshl_add_u64 v[140:141], s[22:23], 0, v[138:139]
	s_add_i32 m0, s38, 0xe000
	s_nop 0
	global_load_lds_dwordx4 v[140:141], off
	s_waitcnt vmcnt(8)
	s_waitcnt lgkmcnt(0)
	s_barrier
	s_setprio 1
	s_waitcnt lgkmcnt(0)
	v_mfma_f32_16x16x32_bf16 v[126:129], v[162:165], v[194:197], v[126:129]
	v_mfma_f32_16x16x32_bf16 v[118:121], v[170:173], v[194:197], v[118:121]
	v_mfma_f32_16x16x32_bf16 v[110:113], v[162:165], v[202:205], v[110:113]
	v_mfma_f32_16x16x32_bf16 v[102:105], v[170:173], v[202:205], v[102:105]
	v_mfma_f32_16x16x32_bf16 v[94:97], v[162:165], v[232:235], v[94:97]
	v_mfma_f32_16x16x32_bf16 v[86:89], v[170:173], v[232:235], v[86:89]
	v_mfma_f32_16x16x32_bf16 v[78:81], v[162:165], v[240:243], v[78:81]
	v_mfma_f32_16x16x32_bf16 v[70:73], v[170:173], v[240:243], v[70:73]
	v_mfma_f32_16x16x32_bf16 v[126:129], v[166:169], v[198:201], v[126:129]
	v_mfma_f32_16x16x32_bf16 v[118:121], v[174:177], v[198:201], v[118:121]
	v_mfma_f32_16x16x32_bf16 v[110:113], v[166:169], v[206:209], v[110:113]
	v_mfma_f32_16x16x32_bf16 v[102:105], v[174:177], v[206:209], v[102:105]
	v_mfma_f32_16x16x32_bf16 v[94:97], v[166:169], v[236:239], v[94:97]
	v_mfma_f32_16x16x32_bf16 v[86:89], v[174:177], v[236:239], v[86:89]
	v_mfma_f32_16x16x32_bf16 v[78:81], v[166:169], v[244:247], v[78:81]
	v_mfma_f32_16x16x32_bf16 v[70:73], v[174:177], v[244:247], v[70:73]
	v_mfma_f32_16x16x32_bf16 v[122:125], v[178:181], v[194:197], v[122:125]
	v_mfma_f32_16x16x32_bf16 v[114:117], v[186:189], v[194:197], v[114:117]
	v_mfma_f32_16x16x32_bf16 v[106:109], v[178:181], v[202:205], v[106:109]
	v_mfma_f32_16x16x32_bf16 v[98:101], v[186:189], v[202:205], v[98:101]
	v_mfma_f32_16x16x32_bf16 v[90:93], v[178:181], v[232:235], v[90:93]
	v_mfma_f32_16x16x32_bf16 v[82:85], v[186:189], v[232:235], v[82:85]
	v_mfma_f32_16x16x32_bf16 v[74:77], v[178:181], v[240:243], v[74:77]
	v_mfma_f32_16x16x32_bf16 v[66:69], v[186:189], v[240:243], v[66:69]
	v_mfma_f32_16x16x32_bf16 v[122:125], v[182:185], v[198:201], v[122:125]
	v_mfma_f32_16x16x32_bf16 v[114:117], v[190:193], v[198:201], v[114:117]
	v_mfma_f32_16x16x32_bf16 v[106:109], v[182:185], v[206:209], v[106:109]
	v_mfma_f32_16x16x32_bf16 v[98:101], v[190:193], v[206:209], v[98:101]
	v_mfma_f32_16x16x32_bf16 v[90:93], v[182:185], v[236:239], v[90:93]
	v_mfma_f32_16x16x32_bf16 v[82:85], v[190:193], v[236:239], v[82:85]
	v_mfma_f32_16x16x32_bf16 v[74:77], v[182:185], v[244:247], v[74:77]
	v_mfma_f32_16x16x32_bf16 v[66:69], v[190:193], v[244:247], v[66:69]
	s_setprio 0
	s_barrier
	s_add_i32 s55, s55, s36
	v_lshl_add_u64 v[140:141], s[24:25], 0, v[0:1]
	s_mov_b32 m0, s55
	ds_read_b128 v[194:197], v145 offset:16384
	ds_read_b128 v[198:201], v145 offset:17408
	ds_read_b128 v[202:205], v145 offset:18432
	ds_read_b128 v[206:209], v145 offset:19456
	ds_read_b128 v[232:235], v145 offset:20480
	ds_read_b128 v[236:239], v145 offset:21504
	ds_read_b128 v[240:243], v145 offset:22528
	ds_read_b128 v[244:247], v145 offset:23552
	global_load_lds_dwordx4 v[140:141], off
	s_add_i32 m0, s55, 0x2000
	s_add_u32 s56, s24, 0x40000
	v_lshl_add_u64 v[210:211], s[24:25], 0, v[130:131]
	s_addc_u32 s57, s25, 0
	s_add_i32 s55, s69, s36
	global_load_lds_dwordx4 v[210:211], off
	v_lshl_add_u64 v[220:221], s[56:57], 0, v[0:1]
	s_mov_b32 m0, s55
	v_lshl_add_u64 v[222:223], s[26:27], 0, v[132:133]
	global_load_lds_dwordx4 v[220:221], off
	v_lshl_add_u64 v[220:221], s[56:57], 0, v[130:131]
	s_add_i32 m0, s55, 0x2000
	s_nop 0
	global_load_lds_dwordx4 v[220:221], off
	v_lshl_add_u64 v[220:221], s[26:27], 0, v[134:135]
	s_mov_b32 m0, s38
	s_nop 0
	global_load_lds_dwordx4 v[220:221], off
	s_mov_b32 m0, s39
	s_nop 0
	global_load_lds_dwordx4 v[222:223], off
	s_waitcnt vmcnt(8)
	s_waitcnt lgkmcnt(0)
	s_barrier
	s_setprio 1
	s_waitcnt lgkmcnt(0)
	v_mfma_f32_16x16x32_bf16 v[62:65], v[162:165], v[194:197], v[62:65]
	v_mfma_f32_16x16x32_bf16 v[54:57], v[170:173], v[194:197], v[54:57]
	v_mfma_f32_16x16x32_bf16 v[46:49], v[162:165], v[202:205], v[46:49]
	v_mfma_f32_16x16x32_bf16 v[38:41], v[170:173], v[202:205], v[38:41]
	v_mfma_f32_16x16x32_bf16 v[30:33], v[162:165], v[232:235], v[30:33]
	v_mfma_f32_16x16x32_bf16 v[22:25], v[170:173], v[232:235], v[22:25]
	v_mfma_f32_16x16x32_bf16 v[14:17], v[162:165], v[240:243], v[14:17]
	v_mfma_f32_16x16x32_bf16 v[6:9], v[170:173], v[240:243], v[6:9]
	v_mfma_f32_16x16x32_bf16 v[62:65], v[166:169], v[198:201], v[62:65]
	v_mfma_f32_16x16x32_bf16 v[54:57], v[174:177], v[198:201], v[54:57]
	v_mfma_f32_16x16x32_bf16 v[46:49], v[166:169], v[206:209], v[46:49]
	v_mfma_f32_16x16x32_bf16 v[38:41], v[174:177], v[206:209], v[38:41]
	v_mfma_f32_16x16x32_bf16 v[30:33], v[166:169], v[236:239], v[30:33]
	v_mfma_f32_16x16x32_bf16 v[22:25], v[174:177], v[236:239], v[22:25]
	v_mfma_f32_16x16x32_bf16 v[14:17], v[166:169], v[244:247], v[14:17]
	v_mfma_f32_16x16x32_bf16 v[6:9], v[174:177], v[244:247], v[6:9]
	v_mfma_f32_16x16x32_bf16 v[58:61], v[178:181], v[194:197], v[58:61]
	v_mfma_f32_16x16x32_bf16 v[50:53], v[186:189], v[194:197], v[50:53]
	v_mfma_f32_16x16x32_bf16 v[42:45], v[178:181], v[202:205], v[42:45]
	v_mfma_f32_16x16x32_bf16 v[34:37], v[186:189], v[202:205], v[34:37]
	v_mfma_f32_16x16x32_bf16 v[26:29], v[178:181], v[232:235], v[26:29]
	v_mfma_f32_16x16x32_bf16 v[18:21], v[186:189], v[232:235], v[18:21]
	v_mfma_f32_16x16x32_bf16 v[10:13], v[178:181], v[240:243], v[10:13]
	v_mfma_f32_16x16x32_bf16 v[2:5], v[186:189], v[240:243], v[2:5]
	v_mfma_f32_16x16x32_bf16 v[58:61], v[182:185], v[198:201], v[58:61]
	v_mfma_f32_16x16x32_bf16 v[50:53], v[190:193], v[198:201], v[50:53]
	v_mfma_f32_16x16x32_bf16 v[42:45], v[182:185], v[206:209], v[42:45]
	v_mfma_f32_16x16x32_bf16 v[34:37], v[190:193], v[206:209], v[34:37]
	v_mfma_f32_16x16x32_bf16 v[26:29], v[182:185], v[236:239], v[26:29]
	v_mfma_f32_16x16x32_bf16 v[18:21], v[190:193], v[236:239], v[18:21]
	v_mfma_f32_16x16x32_bf16 v[10:13], v[182:185], v[244:247], v[10:13]
	v_mfma_f32_16x16x32_bf16 v[2:5], v[190:193], v[244:247], v[2:5]
	s_setprio 0
	s_barrier
	s_add_i32 s55, 0, 0x18000
	v_add_u32_e32 v146, s55, v143
	s_add_i32 s56, 0, 0x1c000
	ds_read_b128 v[162:165], v146
	ds_read_b128 v[166:169], v146 offset:1024
	ds_read_b128 v[170:173], v146 offset:2048
	ds_read_b128 v[174:177], v146 offset:3072
	v_add_u32_e32 v146, s56, v143
	ds_read_b128 v[178:181], v146
	ds_read_b128 v[182:185], v146 offset:1024
	ds_read_b128 v[186:189], v146 offset:2048
	ds_read_b128 v[190:193], v146 offset:3072
	s_add_u32 s26, s26, 0x40000
	s_addc_u32 s27, s27, 0
	s_mov_b32 m0, s40
	v_lshl_add_u64 v[248:249], s[26:27], 0, v[134:135]
	ds_read_b128 v[194:197], v145 offset:32768
	ds_read_b128 v[198:201], v145 offset:33792
	ds_read_b128 v[202:205], v145 offset:34816
	ds_read_b128 v[206:209], v145 offset:35840
	ds_read_b128 v[232:235], v145 offset:36864
	ds_read_b128 v[236:239], v145 offset:37888
	ds_read_b128 v[240:243], v145 offset:38912
	ds_read_b128 v[244:247], v145 offset:39936
	global_load_lds_dwordx4 v[248:249], off
	v_lshl_add_u64 v[248:249], s[26:27], 0, v[132:133]
	s_mov_b32 m0, s41
	s_nop 0
	global_load_lds_dwordx4 v[248:249], off
	s_waitcnt vmcnt(8)
	s_waitcnt lgkmcnt(0)
	s_barrier
	s_setprio 1
	s_waitcnt lgkmcnt(0)
	v_mfma_f32_16x16x32_bf16 v[126:129], v[162:165], v[194:197], v[126:129]
	v_mfma_f32_16x16x32_bf16 v[118:121], v[170:173], v[194:197], v[118:121]
	v_mfma_f32_16x16x32_bf16 v[110:113], v[162:165], v[202:205], v[110:113]
	v_mfma_f32_16x16x32_bf16 v[102:105], v[170:173], v[202:205], v[102:105]
	v_mfma_f32_16x16x32_bf16 v[94:97], v[162:165], v[232:235], v[94:97]
	v_mfma_f32_16x16x32_bf16 v[86:89], v[170:173], v[232:235], v[86:89]
	v_mfma_f32_16x16x32_bf16 v[78:81], v[162:165], v[240:243], v[78:81]
	v_mfma_f32_16x16x32_bf16 v[70:73], v[170:173], v[240:243], v[70:73]
	v_mfma_f32_16x16x32_bf16 v[126:129], v[166:169], v[198:201], v[126:129]
	v_mfma_f32_16x16x32_bf16 v[118:121], v[174:177], v[198:201], v[118:121]
	v_mfma_f32_16x16x32_bf16 v[110:113], v[166:169], v[206:209], v[110:113]
	v_mfma_f32_16x16x32_bf16 v[102:105], v[174:177], v[206:209], v[102:105]
	v_mfma_f32_16x16x32_bf16 v[94:97], v[166:169], v[236:239], v[94:97]
	v_mfma_f32_16x16x32_bf16 v[86:89], v[174:177], v[236:239], v[86:89]
	v_mfma_f32_16x16x32_bf16 v[78:81], v[166:169], v[244:247], v[78:81]
	v_mfma_f32_16x16x32_bf16 v[70:73], v[174:177], v[244:247], v[70:73]
	v_mfma_f32_16x16x32_bf16 v[122:125], v[178:181], v[194:197], v[122:125]
	v_mfma_f32_16x16x32_bf16 v[114:117], v[186:189], v[194:197], v[114:117]
	v_mfma_f32_16x16x32_bf16 v[106:109], v[178:181], v[202:205], v[106:109]
	v_mfma_f32_16x16x32_bf16 v[98:101], v[186:189], v[202:205], v[98:101]
	v_mfma_f32_16x16x32_bf16 v[90:93], v[178:181], v[232:235], v[90:93]
	v_mfma_f32_16x16x32_bf16 v[82:85], v[186:189], v[232:235], v[82:85]
	v_mfma_f32_16x16x32_bf16 v[74:77], v[178:181], v[240:243], v[74:77]
	v_mfma_f32_16x16x32_bf16 v[66:69], v[186:189], v[240:243], v[66:69]
	v_mfma_f32_16x16x32_bf16 v[122:125], v[182:185], v[198:201], v[122:125]
	v_mfma_f32_16x16x32_bf16 v[114:117], v[190:193], v[198:201], v[114:117]
	v_mfma_f32_16x16x32_bf16 v[106:109], v[182:185], v[206:209], v[106:109]
	v_mfma_f32_16x16x32_bf16 v[98:101], v[190:193], v[206:209], v[98:101]
	v_mfma_f32_16x16x32_bf16 v[90:93], v[182:185], v[236:239], v[90:93]
	v_mfma_f32_16x16x32_bf16 v[82:85], v[190:193], v[236:239], v[82:85]
	v_mfma_f32_16x16x32_bf16 v[74:77], v[182:185], v[244:247], v[74:77]
	v_mfma_f32_16x16x32_bf16 v[66:69], v[190:193], v[244:247], v[66:69]
	s_setprio 0
	s_barrier
	s_add_i32 s26, s55, s36
	v_lshl_add_u64 v[140:141], v[140:141], 0, s[90:91]
	s_mov_b32 m0, s26
	ds_read_b128 v[194:197], v145 offset:49152
	ds_read_b128 v[198:201], v145 offset:50176
	ds_read_b128 v[202:205], v145 offset:51200
	ds_read_b128 v[206:209], v145 offset:52224
	ds_read_b128 v[232:235], v145 offset:53248
	ds_read_b128 v[236:239], v145 offset:54272
	ds_read_b128 v[240:243], v145 offset:55296
	ds_read_b128 v[244:247], v145 offset:56320
	global_load_lds_dwordx4 v[140:141], off
	s_add_i32 m0, s26, 0x2000
	s_add_u32 s24, s24, 0x40080
	v_lshl_add_u64 v[140:141], v[210:211], 0, s[90:91]
	s_addc_u32 s25, s25, 0
	s_add_i32 s26, s56, s36
	global_load_lds_dwordx4 v[140:141], off
	v_lshl_add_u64 v[140:141], s[24:25], 0, v[0:1]
	s_mov_b32 m0, s26
	s_nop 0
	global_load_lds_dwordx4 v[140:141], off
	v_lshl_add_u64 v[140:141], s[24:25], 0, v[130:131]
	s_add_i32 m0, s26, 0x2000
	s_nop 0
	global_load_lds_dwordx4 v[140:141], off
	v_lshl_add_u64 v[140:141], v[220:221], 0, s[90:91]
	s_mov_b32 m0, s42
	s_nop 0
	global_load_lds_dwordx4 v[140:141], off
	v_lshl_add_u64 v[140:141], v[222:223], 0, s[90:91]
	s_mov_b32 m0, s43
	s_nop 0
	global_load_lds_dwordx4 v[140:141], off
	s_waitcnt vmcnt(8)
	s_waitcnt lgkmcnt(0)
	s_barrier
	s_setprio 1
	s_waitcnt lgkmcnt(0)
	v_mfma_f32_16x16x32_bf16 v[62:65], v[162:165], v[194:197], v[62:65]
	v_mfma_f32_16x16x32_bf16 v[54:57], v[170:173], v[194:197], v[54:57]
	v_mfma_f32_16x16x32_bf16 v[46:49], v[162:165], v[202:205], v[46:49]
	v_mfma_f32_16x16x32_bf16 v[38:41], v[170:173], v[202:205], v[38:41]
	v_mfma_f32_16x16x32_bf16 v[30:33], v[162:165], v[232:235], v[30:33]
	v_mfma_f32_16x16x32_bf16 v[22:25], v[170:173], v[232:235], v[22:25]
	v_mfma_f32_16x16x32_bf16 v[14:17], v[162:165], v[240:243], v[14:17]
	v_mfma_f32_16x16x32_bf16 v[6:9], v[170:173], v[240:243], v[6:9]
	v_mfma_f32_16x16x32_bf16 v[62:65], v[166:169], v[198:201], v[62:65]
	v_mfma_f32_16x16x32_bf16 v[54:57], v[174:177], v[198:201], v[54:57]
	v_mfma_f32_16x16x32_bf16 v[46:49], v[166:169], v[206:209], v[46:49]
	v_mfma_f32_16x16x32_bf16 v[38:41], v[174:177], v[206:209], v[38:41]
	v_mfma_f32_16x16x32_bf16 v[30:33], v[166:169], v[236:239], v[30:33]
	v_mfma_f32_16x16x32_bf16 v[22:25], v[174:177], v[236:239], v[22:25]
	v_mfma_f32_16x16x32_bf16 v[14:17], v[166:169], v[244:247], v[14:17]
	v_mfma_f32_16x16x32_bf16 v[6:9], v[174:177], v[244:247], v[6:9]
	v_mfma_f32_16x16x32_bf16 v[58:61], v[178:181], v[194:197], v[58:61]
	v_mfma_f32_16x16x32_bf16 v[50:53], v[186:189], v[194:197], v[50:53]
	v_mfma_f32_16x16x32_bf16 v[42:45], v[178:181], v[202:205], v[42:45]
	v_mfma_f32_16x16x32_bf16 v[34:37], v[186:189], v[202:205], v[34:37]
	v_mfma_f32_16x16x32_bf16 v[26:29], v[178:181], v[232:235], v[26:29]
	v_mfma_f32_16x16x32_bf16 v[18:21], v[186:189], v[232:235], v[18:21]
	v_mfma_f32_16x16x32_bf16 v[10:13], v[178:181], v[240:243], v[10:13]
	v_mfma_f32_16x16x32_bf16 v[2:5], v[186:189], v[240:243], v[2:5]
	v_mfma_f32_16x16x32_bf16 v[58:61], v[182:185], v[198:201], v[58:61]
	v_mfma_f32_16x16x32_bf16 v[50:53], v[190:193], v[198:201], v[50:53]
	v_mfma_f32_16x16x32_bf16 v[42:45], v[182:185], v[206:209], v[42:45]
	v_mfma_f32_16x16x32_bf16 v[34:37], v[190:193], v[206:209], v[34:37]
	v_mfma_f32_16x16x32_bf16 v[26:29], v[182:185], v[236:239], v[26:29]
	v_mfma_f32_16x16x32_bf16 v[18:21], v[190:193], v[236:239], v[18:21]
	v_mfma_f32_16x16x32_bf16 v[10:13], v[182:185], v[244:247], v[10:13]
	v_mfma_f32_16x16x32_bf16 v[2:5], v[190:193], v[244:247], v[2:5]
	s_setprio 0
	s_barrier
	s_add_i32 s54, s54, 2
	s_add_u32 s22, s22, 0x100
	s_addc_u32 s23, s23, 0
	s_add_u32 s52, s52, 0x100
	s_addc_u32 s53, s53, 0
	s_cmp_gt_u32 s54, 13
	s_cbranch_scc0 .LBB0_194
	s_and_b64 vcc, exec, s[10:11]
	s_cbranch_vccz .LBB0_197
	s_barrier

.LBB0_274:
	s_add_u32 s16, s14, 0x100
	s_addc_u32 s17, s15, 0
	s_add_i32 s47, 0, 0x10000
	s_cmp_eq_u32 s46, 40
	s_cselect_b32 s21, s7, s17
	s_cselect_b32 s20, s6, s16
	v_add_u32_e32 v140, s47, v143
	s_cselect_b32 s19, s13, s45
	s_cselect_b32 s18, s12, s44
	s_add_i32 s52, 0, 0x14000
	ds_read_b128 v[136:139], v140
	ds_read_b128 v[162:165], v140 offset:1024
	ds_read_b128 v[166:169], v140 offset:2048
	ds_read_b128 v[170:173], v140 offset:3072
	v_add_u32_e32 v140, s52, v143
	ds_read_b128 v[174:177], v140
	ds_read_b128 v[178:181], v140 offset:1024
	ds_read_b128 v[182:185], v140 offset:2048
	ds_read_b128 v[186:189], v140 offset:3072
	v_lshl_add_u64 v[140:141], s[14:15], 0, v[132:133]
	s_add_i32 m0, s30, 0xc000
	ds_read_b128 v[190:193], v145
	ds_read_b128 v[194:197], v145 offset:1024
	ds_read_b128 v[198:201], v145 offset:2048
	ds_read_b128 v[202:205], v145 offset:3072
	ds_read_b128 v[206:209], v145 offset:4096
	ds_read_b128 v[232:235], v145 offset:5120
	ds_read_b128 v[236:239], v145 offset:6144
	ds_read_b128 v[240:243], v145 offset:7168
	global_load_lds_dwordx4 v[140:141], off
	v_lshl_add_u64 v[140:141], s[14:15], 0, v[134:135]
	s_add_i32 m0, s30, 0xe000
	s_nop 0
	global_load_lds_dwordx4 v[140:141], off
	s_waitcnt vmcnt(8)
	s_waitcnt lgkmcnt(0)
	s_barrier
	s_setprio 1
	s_waitcnt lgkmcnt(0)
	v_mfma_f32_16x16x32_bf16 v[126:129], v[136:139], v[190:193], v[126:129]
	v_mfma_f32_16x16x32_bf16 v[122:125], v[166:169], v[190:193], v[122:125]
	v_mfma_f32_16x16x32_bf16 v[110:113], v[136:139], v[198:201], v[110:113]
	v_mfma_f32_16x16x32_bf16 v[106:109], v[166:169], v[198:201], v[106:109]
	v_mfma_f32_16x16x32_bf16 v[94:97], v[136:139], v[206:209], v[94:97]
	v_mfma_f32_16x16x32_bf16 v[90:93], v[166:169], v[206:209], v[90:93]
	v_mfma_f32_16x16x32_bf16 v[78:81], v[136:139], v[236:239], v[78:81]
	v_mfma_f32_16x16x32_bf16 v[74:77], v[166:169], v[236:239], v[74:77]
	v_mfma_f32_16x16x32_bf16 v[126:129], v[162:165], v[194:197], v[126:129]
	v_mfma_f32_16x16x32_bf16 v[122:125], v[170:173], v[194:197], v[122:125]
	v_mfma_f32_16x16x32_bf16 v[110:113], v[162:165], v[202:205], v[110:113]
	v_mfma_f32_16x16x32_bf16 v[106:109], v[170:173], v[202:205], v[106:109]
	v_mfma_f32_16x16x32_bf16 v[94:97], v[162:165], v[232:235], v[94:97]
	v_mfma_f32_16x16x32_bf16 v[90:93], v[170:173], v[232:235], v[90:93]
	v_mfma_f32_16x16x32_bf16 v[78:81], v[162:165], v[240:243], v[78:81]
	v_mfma_f32_16x16x32_bf16 v[74:77], v[170:173], v[240:243], v[74:77]
	v_mfma_f32_16x16x32_bf16 v[118:121], v[174:177], v[190:193], v[118:121]
	v_mfma_f32_16x16x32_bf16 v[114:117], v[182:185], v[190:193], v[114:117]
	v_mfma_f32_16x16x32_bf16 v[102:105], v[174:177], v[198:201], v[102:105]
	v_mfma_f32_16x16x32_bf16 v[98:101], v[182:185], v[198:201], v[98:101]
	v_mfma_f32_16x16x32_bf16 v[86:89], v[174:177], v[206:209], v[86:89]
	v_mfma_f32_16x16x32_bf16 v[82:85], v[182:185], v[206:209], v[82:85]
	v_mfma_f32_16x16x32_bf16 v[70:73], v[174:177], v[236:239], v[70:73]
	v_mfma_f32_16x16x32_bf16 v[66:69], v[182:185], v[236:239], v[66:69]
	v_mfma_f32_16x16x32_bf16 v[118:121], v[178:181], v[194:197], v[118:121]
	v_mfma_f32_16x16x32_bf16 v[114:117], v[186:189], v[194:197], v[114:117]
	v_mfma_f32_16x16x32_bf16 v[102:105], v[178:181], v[202:205], v[102:105]
	v_mfma_f32_16x16x32_bf16 v[98:101], v[186:189], v[202:205], v[98:101]
	v_mfma_f32_16x16x32_bf16 v[86:89], v[178:181], v[232:235], v[86:89]
	v_mfma_f32_16x16x32_bf16 v[82:85], v[186:189], v[232:235], v[82:85]
	v_mfma_f32_16x16x32_bf16 v[70:73], v[178:181], v[240:243], v[70:73]
	v_mfma_f32_16x16x32_bf16 v[66:69], v[186:189], v[240:243], v[66:69]
	s_setprio 0
	s_barrier
	s_add_i32 s14, s47, s29
	v_lshl_add_u64 v[140:141], s[18:19], 0, v[0:1]
	s_mov_b32 m0, s14
	ds_read_b128 v[190:193], v145 offset:16384
	ds_read_b128 v[194:197], v145 offset:17408
	ds_read_b128 v[198:201], v145 offset:18432
	ds_read_b128 v[202:205], v145 offset:19456
	ds_read_b128 v[206:209], v145 offset:20480
	ds_read_b128 v[232:235], v145 offset:21504
	ds_read_b128 v[236:239], v145 offset:22528
	ds_read_b128 v[240:243], v145 offset:23552
	global_load_lds_dwordx4 v[140:141], off
	s_add_i32 m0, s14, 0x2000
	s_add_u32 s14, s18, 0xb0000
	v_lshl_add_u64 v[210:211], s[18:19], 0, v[130:131]
	s_addc_u32 s15, s19, 0
	s_add_i32 s47, s52, s29
	global_load_lds_dwordx4 v[210:211], off
	v_lshl_add_u64 v[220:221], s[14:15], 0, v[0:1]
	s_mov_b32 m0, s47
	v_lshl_add_u64 v[222:223], s[20:21], 0, v[130:131]
	global_load_lds_dwordx4 v[220:221], off
	v_lshl_add_u64 v[220:221], s[14:15], 0, v[130:131]
	s_add_i32 m0, s47, 0x2000
	s_nop 0
	global_load_lds_dwordx4 v[220:221], off
	v_lshl_add_u64 v[220:221], s[20:21], 0, v[0:1]
	s_mov_b32 m0, s30
	s_nop 0
	global_load_lds_dwordx4 v[220:221], off
	s_mov_b32 m0, s31
	s_nop 0
	global_load_lds_dwordx4 v[222:223], off
	s_waitcnt vmcnt(8)
	s_waitcnt lgkmcnt(0)
	s_barrier
	s_setprio 1
	s_waitcnt lgkmcnt(0)
	v_mfma_f32_16x16x32_bf16 v[62:65], v[136:139], v[190:193], v[62:65]
	v_mfma_f32_16x16x32_bf16 v[58:61], v[166:169], v[190:193], v[58:61]
	v_mfma_f32_16x16x32_bf16 v[46:49], v[136:139], v[198:201], v[46:49]
	v_mfma_f32_16x16x32_bf16 v[42:45], v[166:169], v[198:201], v[42:45]
	v_mfma_f32_16x16x32_bf16 v[30:33], v[136:139], v[206:209], v[30:33]
	v_mfma_f32_16x16x32_bf16 v[26:29], v[166:169], v[206:209], v[26:29]
	v_mfma_f32_16x16x32_bf16 v[14:17], v[136:139], v[236:239], v[14:17]
	v_mfma_f32_16x16x32_bf16 v[10:13], v[166:169], v[236:239], v[10:13]
	v_mfma_f32_16x16x32_bf16 v[62:65], v[162:165], v[194:197], v[62:65]
	v_mfma_f32_16x16x32_bf16 v[58:61], v[170:173], v[194:197], v[58:61]
	v_mfma_f32_16x16x32_bf16 v[46:49], v[162:165], v[202:205], v[46:49]
	v_mfma_f32_16x16x32_bf16 v[42:45], v[170:173], v[202:205], v[42:45]
	v_mfma_f32_16x16x32_bf16 v[30:33], v[162:165], v[232:235], v[30:33]
	v_mfma_f32_16x16x32_bf16 v[26:29], v[170:173], v[232:235], v[26:29]
	v_mfma_f32_16x16x32_bf16 v[14:17], v[162:165], v[240:243], v[14:17]
	v_mfma_f32_16x16x32_bf16 v[10:13], v[170:173], v[240:243], v[10:13]
	v_mfma_f32_16x16x32_bf16 v[54:57], v[174:177], v[190:193], v[54:57]
	v_mfma_f32_16x16x32_bf16 v[50:53], v[182:185], v[190:193], v[50:53]
	v_mfma_f32_16x16x32_bf16 v[38:41], v[174:177], v[198:201], v[38:41]
	v_mfma_f32_16x16x32_bf16 v[34:37], v[182:185], v[198:201], v[34:37]
	v_mfma_f32_16x16x32_bf16 v[22:25], v[174:177], v[206:209], v[22:25]
	v_mfma_f32_16x16x32_bf16 v[18:21], v[182:185], v[206:209], v[18:21]
	v_mfma_f32_16x16x32_bf16 v[6:9], v[174:177], v[236:239], v[6:9]
	v_mfma_f32_16x16x32_bf16 v[2:5], v[182:185], v[236:239], v[2:5]
	v_mfma_f32_16x16x32_bf16 v[54:57], v[178:181], v[194:197], v[54:57]
	v_mfma_f32_16x16x32_bf16 v[50:53], v[186:189], v[194:197], v[50:53]
	v_mfma_f32_16x16x32_bf16 v[38:41], v[178:181], v[202:205], v[38:41]
	v_mfma_f32_16x16x32_bf16 v[34:37], v[186:189], v[202:205], v[34:37]
	v_mfma_f32_16x16x32_bf16 v[22:25], v[178:181], v[232:235], v[22:25]
	v_mfma_f32_16x16x32_bf16 v[18:21], v[186:189], v[232:235], v[18:21]
	v_mfma_f32_16x16x32_bf16 v[6:9], v[178:181], v[240:243], v[6:9]
	v_mfma_f32_16x16x32_bf16 v[2:5], v[186:189], v[240:243], v[2:5]
	s_setprio 0
	s_barrier
	s_add_i32 s47, 0, 0x18000
	v_add_u32_e32 v146, s47, v143
	s_add_i32 s52, 0, 0x1c000
	ds_read_b128 v[136:139], v146
	ds_read_b128 v[162:165], v146 offset:1024
	ds_read_b128 v[166:169], v146 offset:2048
	ds_read_b128 v[170:173], v146 offset:3072
	v_add_u32_e32 v146, s52, v143
	ds_read_b128 v[174:177], v146
	ds_read_b128 v[178:181], v146 offset:1024
	ds_read_b128 v[182:185], v146 offset:2048
	ds_read_b128 v[186:189], v146 offset:3072
	s_add_u32 s14, s20, 0xb0000
	s_addc_u32 s15, s21, 0
	s_mov_b32 m0, s34
	v_lshl_add_u64 v[244:245], s[14:15], 0, v[0:1]
	ds_read_b128 v[190:193], v145 offset:32768
	ds_read_b128 v[194:197], v145 offset:33792
	ds_read_b128 v[198:201], v145 offset:34816
	ds_read_b128 v[202:205], v145 offset:35840
	ds_read_b128 v[206:209], v145 offset:36864
	ds_read_b128 v[232:235], v145 offset:37888
	ds_read_b128 v[236:239], v145 offset:38912
	ds_read_b128 v[240:243], v145 offset:39936
	global_load_lds_dwordx4 v[244:245], off
	v_lshl_add_u64 v[244:245], s[14:15], 0, v[130:131]
	s_mov_b32 m0, s35
	s_nop 0
	global_load_lds_dwordx4 v[244:245], off
	s_waitcnt vmcnt(8)
	s_waitcnt lgkmcnt(0)
	s_barrier
	s_setprio 1
	s_waitcnt lgkmcnt(0)
	v_mfma_f32_16x16x32_bf16 v[126:129], v[136:139], v[190:193], v[126:129]
	v_mfma_f32_16x16x32_bf16 v[122:125], v[166:169], v[190:193], v[122:125]
	v_mfma_f32_16x16x32_bf16 v[110:113], v[136:139], v[198:201], v[110:113]
	v_mfma_f32_16x16x32_bf16 v[106:109], v[166:169], v[198:201], v[106:109]
	v_mfma_f32_16x16x32_bf16 v[94:97], v[136:139], v[206:209], v[94:97]
	v_mfma_f32_16x16x32_bf16 v[90:93], v[166:169], v[206:209], v[90:93]
	v_mfma_f32_16x16x32_bf16 v[78:81], v[136:139], v[236:239], v[78:81]
	v_mfma_f32_16x16x32_bf16 v[74:77], v[166:169], v[236:239], v[74:77]
	v_mfma_f32_16x16x32_bf16 v[126:129], v[162:165], v[194:197], v[126:129]
	v_mfma_f32_16x16x32_bf16 v[122:125], v[170:173], v[194:197], v[122:125]
	v_mfma_f32_16x16x32_bf16 v[110:113], v[162:165], v[202:205], v[110:113]
	v_mfma_f32_16x16x32_bf16 v[106:109], v[170:173], v[202:205], v[106:109]
	v_mfma_f32_16x16x32_bf16 v[94:97], v[162:165], v[232:235], v[94:97]
	v_mfma_f32_16x16x32_bf16 v[90:93], v[170:173], v[232:235], v[90:93]
	v_mfma_f32_16x16x32_bf16 v[78:81], v[162:165], v[240:243], v[78:81]
	v_mfma_f32_16x16x32_bf16 v[74:77], v[170:173], v[240:243], v[74:77]
	v_mfma_f32_16x16x32_bf16 v[118:121], v[174:177], v[190:193], v[118:121]
	v_mfma_f32_16x16x32_bf16 v[114:117], v[182:185], v[190:193], v[114:117]
	v_mfma_f32_16x16x32_bf16 v[102:105], v[174:177], v[198:201], v[102:105]
	v_mfma_f32_16x16x32_bf16 v[98:101], v[182:185], v[198:201], v[98:101]
	v_mfma_f32_16x16x32_bf16 v[86:89], v[174:177], v[206:209], v[86:89]
	v_mfma_f32_16x16x32_bf16 v[82:85], v[182:185], v[206:209], v[82:85]
	v_mfma_f32_16x16x32_bf16 v[70:73], v[174:177], v[236:239], v[70:73]
	v_mfma_f32_16x16x32_bf16 v[66:69], v[182:185], v[236:239], v[66:69]
	v_mfma_f32_16x16x32_bf16 v[118:121], v[178:181], v[194:197], v[118:121]
	v_mfma_f32_16x16x32_bf16 v[114:117], v[186:189], v[194:197], v[114:117]
	v_mfma_f32_16x16x32_bf16 v[102:105], v[178:181], v[202:205], v[102:105]
	v_mfma_f32_16x16x32_bf16 v[98:101], v[186:189], v[202:205], v[98:101]
	v_mfma_f32_16x16x32_bf16 v[86:89], v[178:181], v[232:235], v[86:89]
	v_mfma_f32_16x16x32_bf16 v[82:85], v[186:189], v[232:235], v[82:85]
	v_mfma_f32_16x16x32_bf16 v[70:73], v[178:181], v[240:243], v[70:73]
	v_mfma_f32_16x16x32_bf16 v[66:69], v[186:189], v[240:243], v[66:69]
	s_setprio 0
	s_barrier
	s_add_i32 s14, s47, s29
	v_lshl_add_u64 v[140:141], v[140:141], 0, s[90:91]
	s_mov_b32 m0, s14
	ds_read_b128 v[190:193], v145 offset:49152
	ds_read_b128 v[194:197], v145 offset:50176
	ds_read_b128 v[198:201], v145 offset:51200
	ds_read_b128 v[202:205], v145 offset:52224
	ds_read_b128 v[206:209], v145 offset:53248
	ds_read_b128 v[232:235], v145 offset:54272
	ds_read_b128 v[236:239], v145 offset:55296
	ds_read_b128 v[240:243], v145 offset:56320
	global_load_lds_dwordx4 v[140:141], off
	s_add_i32 m0, s14, 0x2000
	s_add_u32 s14, s18, 0xb0080
	v_lshl_add_u64 v[140:141], v[210:211], 0, s[90:91]
	s_addc_u32 s15, s19, 0
	s_add_i32 s18, s52, s29
	global_load_lds_dwordx4 v[140:141], off
	v_lshl_add_u64 v[140:141], s[14:15], 0, v[0:1]
	s_mov_b32 m0, s18
	s_nop 0
	global_load_lds_dwordx4 v[140:141], off
	v_lshl_add_u64 v[140:141], s[14:15], 0, v[130:131]
	s_add_i32 m0, s18, 0x2000
	s_nop 0
	global_load_lds_dwordx4 v[140:141], off
	v_lshl_add_u64 v[140:141], v[220:221], 0, s[90:91]
	s_mov_b32 m0, s36
	s_nop 0
	global_load_lds_dwordx4 v[140:141], off
	v_lshl_add_u64 v[140:141], v[222:223], 0, s[90:91]
	s_mov_b32 m0, s37
	s_nop 0
	global_load_lds_dwordx4 v[140:141], off
	s_waitcnt vmcnt(8)
	s_waitcnt lgkmcnt(0)
	s_barrier
	s_setprio 1
	s_waitcnt lgkmcnt(0)
	v_mfma_f32_16x16x32_bf16 v[62:65], v[136:139], v[190:193], v[62:65]
	v_mfma_f32_16x16x32_bf16 v[58:61], v[166:169], v[190:193], v[58:61]
	v_mfma_f32_16x16x32_bf16 v[46:49], v[136:139], v[198:201], v[46:49]
	v_mfma_f32_16x16x32_bf16 v[42:45], v[166:169], v[198:201], v[42:45]
	v_mfma_f32_16x16x32_bf16 v[30:33], v[136:139], v[206:209], v[30:33]
	v_mfma_f32_16x16x32_bf16 v[26:29], v[166:169], v[206:209], v[26:29]
	v_mfma_f32_16x16x32_bf16 v[14:17], v[136:139], v[236:239], v[14:17]
	v_mfma_f32_16x16x32_bf16 v[10:13], v[166:169], v[236:239], v[10:13]
	v_mfma_f32_16x16x32_bf16 v[62:65], v[162:165], v[194:197], v[62:65]
	v_mfma_f32_16x16x32_bf16 v[58:61], v[170:173], v[194:197], v[58:61]
	v_mfma_f32_16x16x32_bf16 v[46:49], v[162:165], v[202:205], v[46:49]
	v_mfma_f32_16x16x32_bf16 v[42:45], v[170:173], v[202:205], v[42:45]
	v_mfma_f32_16x16x32_bf16 v[30:33], v[162:165], v[232:235], v[30:33]
	v_mfma_f32_16x16x32_bf16 v[26:29], v[170:173], v[232:235], v[26:29]
	v_mfma_f32_16x16x32_bf16 v[14:17], v[162:165], v[240:243], v[14:17]
	v_mfma_f32_16x16x32_bf16 v[10:13], v[170:173], v[240:243], v[10:13]
	v_mfma_f32_16x16x32_bf16 v[54:57], v[174:177], v[190:193], v[54:57]
	v_mfma_f32_16x16x32_bf16 v[50:53], v[182:185], v[190:193], v[50:53]
	v_mfma_f32_16x16x32_bf16 v[38:41], v[174:177], v[198:201], v[38:41]
	v_mfma_f32_16x16x32_bf16 v[34:37], v[182:185], v[198:201], v[34:37]
	v_mfma_f32_16x16x32_bf16 v[22:25], v[174:177], v[206:209], v[22:25]
	v_mfma_f32_16x16x32_bf16 v[18:21], v[182:185], v[206:209], v[18:21]
	v_mfma_f32_16x16x32_bf16 v[6:9], v[174:177], v[236:239], v[6:9]
	v_mfma_f32_16x16x32_bf16 v[2:5], v[182:185], v[236:239], v[2:5]
	v_mfma_f32_16x16x32_bf16 v[54:57], v[178:181], v[194:197], v[54:57]
	v_mfma_f32_16x16x32_bf16 v[50:53], v[186:189], v[194:197], v[50:53]
	v_mfma_f32_16x16x32_bf16 v[38:41], v[178:181], v[202:205], v[38:41]
	v_mfma_f32_16x16x32_bf16 v[34:37], v[186:189], v[202:205], v[34:37]
	v_mfma_f32_16x16x32_bf16 v[22:25], v[178:181], v[232:235], v[22:25]
	v_mfma_f32_16x16x32_bf16 v[18:21], v[186:189], v[232:235], v[18:21]
	v_mfma_f32_16x16x32_bf16 v[6:9], v[178:181], v[240:243], v[6:9]
	v_mfma_f32_16x16x32_bf16 v[2:5], v[186:189], v[240:243], v[2:5]
	s_setprio 0
	s_barrier
	s_add_i32 s46, s46, 2
	s_add_u32 s44, s44, 0x100
	s_addc_u32 s45, s45, 0
	s_cmp_gt_u32 s46, 41
	s_mov_b64 s[14:15], s[16:17]
	s_cbranch_scc0 .LBB0_274
	s_and_b64 vcc, exec, s[10:11]
	s_cbranch_vccz .LBB0_277
	s_barrier

.LBB0_405:
	s_add_u32 s30, s28, 0xfffc0080
	s_addc_u32 s31, s29, -1
	s_add_i32 s56, 0, 0x10000
	s_cmp_eq_u32 s75, 12
	s_cselect_b32 s35, s21, s31
	s_cselect_b32 s34, s71, s30
	v_add_u32_e32 v140, s56, v143
	s_cselect_b32 s31, s19, s74
	s_cselect_b32 s30, s72, s73
	s_add_i32 s76, 0, 0x14000
	ds_read_b128 v[162:165], v140
	ds_read_b128 v[166:169], v140 offset:1024
	ds_read_b128 v[170:173], v140 offset:2048
	ds_read_b128 v[174:177], v140 offset:3072
	v_add_u32_e32 v140, s76, v143
	ds_read_b128 v[178:181], v140
	ds_read_b128 v[182:185], v140 offset:1024
	ds_read_b128 v[186:189], v140 offset:2048
	ds_read_b128 v[190:193], v140 offset:3072
	v_lshl_add_u64 v[140:141], s[28:29], 0, v[136:137]
	s_add_i32 m0, s25, 0xc000
	ds_read_b128 v[194:197], v145
	ds_read_b128 v[198:201], v145 offset:1024
	ds_read_b128 v[202:205], v145 offset:2048
	ds_read_b128 v[206:209], v145 offset:3072
	ds_read_b128 v[232:235], v145 offset:4096
	ds_read_b128 v[236:239], v145 offset:5120
	ds_read_b128 v[240:243], v145 offset:6144
	ds_read_b128 v[244:247], v145 offset:7168
	global_load_lds_dwordx4 v[140:141], off
	v_lshl_add_u64 v[140:141], s[28:29], 0, v[138:139]
	s_add_i32 m0, s25, 0xe000
	s_nop 0
	global_load_lds_dwordx4 v[140:141], off
	s_waitcnt vmcnt(8)
	s_waitcnt lgkmcnt(0)
	s_barrier
	s_setprio 1
	s_waitcnt lgkmcnt(0)
	v_mfma_f32_16x16x32_bf16 v[126:129], v[162:165], v[194:197], v[126:129]
	v_mfma_f32_16x16x32_bf16 v[122:125], v[170:173], v[194:197], v[122:125]
	v_mfma_f32_16x16x32_bf16 v[118:121], v[162:165], v[202:205], v[118:121]
	v_mfma_f32_16x16x32_bf16 v[110:113], v[170:173], v[202:205], v[110:113]
	v_mfma_f32_16x16x32_bf16 v[102:105], v[162:165], v[232:235], v[102:105]
	v_mfma_f32_16x16x32_bf16 v[94:97], v[170:173], v[232:235], v[94:97]
	v_mfma_f32_16x16x32_bf16 v[86:89], v[162:165], v[240:243], v[86:89]
	v_mfma_f32_16x16x32_bf16 v[78:81], v[170:173], v[240:243], v[78:81]
	v_mfma_f32_16x16x32_bf16 v[126:129], v[166:169], v[198:201], v[126:129]
	v_mfma_f32_16x16x32_bf16 v[122:125], v[174:177], v[198:201], v[122:125]
	v_mfma_f32_16x16x32_bf16 v[118:121], v[166:169], v[206:209], v[118:121]
	v_mfma_f32_16x16x32_bf16 v[110:113], v[174:177], v[206:209], v[110:113]
	v_mfma_f32_16x16x32_bf16 v[102:105], v[166:169], v[236:239], v[102:105]
	v_mfma_f32_16x16x32_bf16 v[94:97], v[174:177], v[236:239], v[94:97]
	v_mfma_f32_16x16x32_bf16 v[86:89], v[166:169], v[244:247], v[86:89]
	v_mfma_f32_16x16x32_bf16 v[78:81], v[174:177], v[244:247], v[78:81]
	v_mfma_f32_16x16x32_bf16 v[114:117], v[178:181], v[194:197], v[114:117]
	v_mfma_f32_16x16x32_bf16 v[106:109], v[186:189], v[194:197], v[106:109]
	v_mfma_f32_16x16x32_bf16 v[98:101], v[178:181], v[202:205], v[98:101]
	v_mfma_f32_16x16x32_bf16 v[90:93], v[186:189], v[202:205], v[90:93]
	v_mfma_f32_16x16x32_bf16 v[82:85], v[178:181], v[232:235], v[82:85]
	v_mfma_f32_16x16x32_bf16 v[74:77], v[186:189], v[232:235], v[74:77]
	v_mfma_f32_16x16x32_bf16 v[70:73], v[178:181], v[240:243], v[70:73]
	v_mfma_f32_16x16x32_bf16 v[66:69], v[186:189], v[240:243], v[66:69]
	v_mfma_f32_16x16x32_bf16 v[114:117], v[182:185], v[198:201], v[114:117]
	v_mfma_f32_16x16x32_bf16 v[106:109], v[190:193], v[198:201], v[106:109]
	v_mfma_f32_16x16x32_bf16 v[98:101], v[182:185], v[206:209], v[98:101]
	v_mfma_f32_16x16x32_bf16 v[90:93], v[190:193], v[206:209], v[90:93]
	v_mfma_f32_16x16x32_bf16 v[82:85], v[182:185], v[236:239], v[82:85]
	v_mfma_f32_16x16x32_bf16 v[74:77], v[190:193], v[236:239], v[74:77]
	v_mfma_f32_16x16x32_bf16 v[70:73], v[182:185], v[244:247], v[70:73]
	v_mfma_f32_16x16x32_bf16 v[66:69], v[190:193], v[244:247], v[66:69]
	s_setprio 0
	s_barrier
	s_add_i32 s56, s56, s13
	v_lshl_add_u64 v[140:141], s[30:31], 0, v[0:1]
	s_mov_b32 m0, s56
	ds_read_b128 v[194:197], v145 offset:16384
	ds_read_b128 v[198:201], v145 offset:17408
	ds_read_b128 v[202:205], v145 offset:18432
	ds_read_b128 v[206:209], v145 offset:19456
	ds_read_b128 v[232:235], v145 offset:20480
	ds_read_b128 v[236:239], v145 offset:21504
	ds_read_b128 v[240:243], v145 offset:22528
	ds_read_b128 v[244:247], v145 offset:23552
	global_load_lds_dwordx4 v[140:141], off
	s_add_i32 m0, s56, 0x2000
	s_add_u32 s56, s30, 0x40000
	v_lshl_add_u64 v[210:211], s[30:31], 0, v[130:131]
	s_addc_u32 s57, s31, 0
	s_add_i32 s76, s76, s13
	global_load_lds_dwordx4 v[210:211], off
	v_lshl_add_u64 v[220:221], s[56:57], 0, v[0:1]
	s_mov_b32 m0, s76
	v_lshl_add_u64 v[222:223], s[34:35], 0, v[132:133]
	global_load_lds_dwordx4 v[220:221], off
	v_lshl_add_u64 v[220:221], s[56:57], 0, v[130:131]
	s_add_i32 m0, s76, 0x2000
	s_nop 0
	global_load_lds_dwordx4 v[220:221], off
	v_lshl_add_u64 v[220:221], s[34:35], 0, v[134:135]
	s_mov_b32 m0, s25
	s_nop 0
	global_load_lds_dwordx4 v[220:221], off
	s_mov_b32 m0, s47
	s_nop 0
	global_load_lds_dwordx4 v[222:223], off
	s_waitcnt vmcnt(8)
	s_waitcnt lgkmcnt(0)
	s_barrier
	s_setprio 1
	s_waitcnt lgkmcnt(0)
	v_mfma_f32_16x16x32_bf16 v[62:65], v[162:165], v[194:197], v[62:65]
	v_mfma_f32_16x16x32_bf16 v[58:61], v[170:173], v[194:197], v[58:61]
	v_mfma_f32_16x16x32_bf16 v[54:57], v[162:165], v[202:205], v[54:57]
	v_mfma_f32_16x16x32_bf16 v[46:49], v[170:173], v[202:205], v[46:49]
	v_mfma_f32_16x16x32_bf16 v[38:41], v[162:165], v[232:235], v[38:41]
	v_mfma_f32_16x16x32_bf16 v[30:33], v[170:173], v[232:235], v[30:33]
	v_mfma_f32_16x16x32_bf16 v[22:25], v[162:165], v[240:243], v[22:25]
	v_mfma_f32_16x16x32_bf16 v[14:17], v[170:173], v[240:243], v[14:17]
	v_mfma_f32_16x16x32_bf16 v[62:65], v[166:169], v[198:201], v[62:65]
	v_mfma_f32_16x16x32_bf16 v[58:61], v[174:177], v[198:201], v[58:61]
	v_mfma_f32_16x16x32_bf16 v[54:57], v[166:169], v[206:209], v[54:57]
	v_mfma_f32_16x16x32_bf16 v[46:49], v[174:177], v[206:209], v[46:49]
	v_mfma_f32_16x16x32_bf16 v[38:41], v[166:169], v[236:239], v[38:41]
	v_mfma_f32_16x16x32_bf16 v[30:33], v[174:177], v[236:239], v[30:33]
	v_mfma_f32_16x16x32_bf16 v[22:25], v[166:169], v[244:247], v[22:25]
	v_mfma_f32_16x16x32_bf16 v[14:17], v[174:177], v[244:247], v[14:17]
	v_mfma_f32_16x16x32_bf16 v[50:53], v[178:181], v[194:197], v[50:53]
	v_mfma_f32_16x16x32_bf16 v[42:45], v[186:189], v[194:197], v[42:45]
	v_mfma_f32_16x16x32_bf16 v[34:37], v[178:181], v[202:205], v[34:37]
	v_mfma_f32_16x16x32_bf16 v[26:29], v[186:189], v[202:205], v[26:29]
	v_mfma_f32_16x16x32_bf16 v[18:21], v[178:181], v[232:235], v[18:21]
	v_mfma_f32_16x16x32_bf16 v[10:13], v[186:189], v[232:235], v[10:13]
	v_mfma_f32_16x16x32_bf16 v[6:9], v[178:181], v[240:243], v[6:9]
	v_mfma_f32_16x16x32_bf16 v[2:5], v[186:189], v[240:243], v[2:5]
	v_mfma_f32_16x16x32_bf16 v[50:53], v[182:185], v[198:201], v[50:53]
	v_mfma_f32_16x16x32_bf16 v[42:45], v[190:193], v[198:201], v[42:45]
	v_mfma_f32_16x16x32_bf16 v[34:37], v[182:185], v[206:209], v[34:37]
	v_mfma_f32_16x16x32_bf16 v[26:29], v[190:193], v[206:209], v[26:29]
	v_mfma_f32_16x16x32_bf16 v[18:21], v[182:185], v[236:239], v[18:21]
	v_mfma_f32_16x16x32_bf16 v[10:13], v[190:193], v[236:239], v[10:13]
	v_mfma_f32_16x16x32_bf16 v[6:9], v[182:185], v[244:247], v[6:9]
	v_mfma_f32_16x16x32_bf16 v[2:5], v[190:193], v[244:247], v[2:5]
	s_setprio 0
	s_barrier
	s_add_i32 s56, 0, 0x18000
	v_add_u32_e32 v146, s56, v143
	s_add_i32 s57, 0, 0x1c000
	ds_read_b128 v[162:165], v146
	ds_read_b128 v[166:169], v146 offset:1024
	ds_read_b128 v[170:173], v146 offset:2048
	ds_read_b128 v[174:177], v146 offset:3072
	v_add_u32_e32 v146, s57, v143
	ds_read_b128 v[178:181], v146
	ds_read_b128 v[182:185], v146 offset:1024
	ds_read_b128 v[186:189], v146 offset:2048
	ds_read_b128 v[190:193], v146 offset:3072
	s_add_u32 s34, s34, 0x40000
	s_addc_u32 s35, s35, 0
	s_mov_b32 m0, s52
	v_lshl_add_u64 v[248:249], s[34:35], 0, v[134:135]
	ds_read_b128 v[194:197], v145 offset:32768
	ds_read_b128 v[198:201], v145 offset:33792
	ds_read_b128 v[202:205], v145 offset:34816
	ds_read_b128 v[206:209], v145 offset:35840
	ds_read_b128 v[232:235], v145 offset:36864
	ds_read_b128 v[236:239], v145 offset:37888
	ds_read_b128 v[240:243], v145 offset:38912
	ds_read_b128 v[244:247], v145 offset:39936
	global_load_lds_dwordx4 v[248:249], off
	v_lshl_add_u64 v[248:249], s[34:35], 0, v[132:133]
	s_mov_b32 m0, s53
	s_nop 0
	global_load_lds_dwordx4 v[248:249], off
	s_waitcnt vmcnt(8)
	s_waitcnt lgkmcnt(0)
	s_barrier
	s_setprio 1
	s_waitcnt lgkmcnt(0)
	v_mfma_f32_16x16x32_bf16 v[126:129], v[162:165], v[194:197], v[126:129]
	v_mfma_f32_16x16x32_bf16 v[122:125], v[170:173], v[194:197], v[122:125]
	v_mfma_f32_16x16x32_bf16 v[118:121], v[162:165], v[202:205], v[118:121]
	v_mfma_f32_16x16x32_bf16 v[110:113], v[170:173], v[202:205], v[110:113]
	v_mfma_f32_16x16x32_bf16 v[102:105], v[162:165], v[232:235], v[102:105]
	v_mfma_f32_16x16x32_bf16 v[94:97], v[170:173], v[232:235], v[94:97]
	v_mfma_f32_16x16x32_bf16 v[86:89], v[162:165], v[240:243], v[86:89]
	v_mfma_f32_16x16x32_bf16 v[78:81], v[170:173], v[240:243], v[78:81]
	v_mfma_f32_16x16x32_bf16 v[126:129], v[166:169], v[198:201], v[126:129]
	v_mfma_f32_16x16x32_bf16 v[122:125], v[174:177], v[198:201], v[122:125]
	v_mfma_f32_16x16x32_bf16 v[118:121], v[166:169], v[206:209], v[118:121]
	v_mfma_f32_16x16x32_bf16 v[110:113], v[174:177], v[206:209], v[110:113]
	v_mfma_f32_16x16x32_bf16 v[102:105], v[166:169], v[236:239], v[102:105]
	v_mfma_f32_16x16x32_bf16 v[94:97], v[174:177], v[236:239], v[94:97]
	v_mfma_f32_16x16x32_bf16 v[86:89], v[166:169], v[244:247], v[86:89]
	v_mfma_f32_16x16x32_bf16 v[78:81], v[174:177], v[244:247], v[78:81]
	v_mfma_f32_16x16x32_bf16 v[114:117], v[178:181], v[194:197], v[114:117]
	v_mfma_f32_16x16x32_bf16 v[106:109], v[186:189], v[194:197], v[106:109]
	v_mfma_f32_16x16x32_bf16 v[98:101], v[178:181], v[202:205], v[98:101]
	v_mfma_f32_16x16x32_bf16 v[90:93], v[186:189], v[202:205], v[90:93]
	v_mfma_f32_16x16x32_bf16 v[82:85], v[178:181], v[232:235], v[82:85]
	v_mfma_f32_16x16x32_bf16 v[74:77], v[186:189], v[232:235], v[74:77]
	v_mfma_f32_16x16x32_bf16 v[70:73], v[178:181], v[240:243], v[70:73]
	v_mfma_f32_16x16x32_bf16 v[66:69], v[186:189], v[240:243], v[66:69]
	v_mfma_f32_16x16x32_bf16 v[114:117], v[182:185], v[198:201], v[114:117]
	v_mfma_f32_16x16x32_bf16 v[106:109], v[190:193], v[198:201], v[106:109]
	v_mfma_f32_16x16x32_bf16 v[98:101], v[182:185], v[206:209], v[98:101]
	v_mfma_f32_16x16x32_bf16 v[90:93], v[190:193], v[206:209], v[90:93]
	v_mfma_f32_16x16x32_bf16 v[82:85], v[182:185], v[236:239], v[82:85]
	v_mfma_f32_16x16x32_bf16 v[74:77], v[190:193], v[236:239], v[74:77]
	v_mfma_f32_16x16x32_bf16 v[70:73], v[182:185], v[244:247], v[70:73]
	v_mfma_f32_16x16x32_bf16 v[66:69], v[190:193], v[244:247], v[66:69]
	s_setprio 0
	s_barrier
	s_add_i32 s34, s56, s13
	v_lshl_add_u64 v[140:141], v[140:141], 0, s[90:91]
	s_mov_b32 m0, s34
	ds_read_b128 v[194:197], v145 offset:49152
	ds_read_b128 v[198:201], v145 offset:50176
	ds_read_b128 v[202:205], v145 offset:51200
	ds_read_b128 v[206:209], v145 offset:52224
	ds_read_b128 v[232:235], v145 offset:53248
	ds_read_b128 v[236:239], v145 offset:54272
	ds_read_b128 v[240:243], v145 offset:55296
	ds_read_b128 v[244:247], v145 offset:56320
	global_load_lds_dwordx4 v[140:141], off
	s_add_i32 m0, s34, 0x2000
	s_add_u32 s30, s30, 0x40080
	v_lshl_add_u64 v[140:141], v[210:211], 0, s[90:91]
	s_addc_u32 s31, s31, 0
	s_add_i32 s34, s57, s13
	global_load_lds_dwordx4 v[140:141], off
	v_lshl_add_u64 v[140:141], s[30:31], 0, v[0:1]
	s_mov_b32 m0, s34
	s_nop 0
	global_load_lds_dwordx4 v[140:141], off
	v_lshl_add_u64 v[140:141], s[30:31], 0, v[130:131]
	s_add_i32 m0, s34, 0x2000
	s_nop 0
	global_load_lds_dwordx4 v[140:141], off
	v_lshl_add_u64 v[140:141], v[220:221], 0, s[90:91]
	s_mov_b32 m0, s54
	s_nop 0
	global_load_lds_dwordx4 v[140:141], off
	v_lshl_add_u64 v[140:141], v[222:223], 0, s[90:91]
	s_mov_b32 m0, s55
	s_nop 0
	global_load_lds_dwordx4 v[140:141], off
	s_waitcnt vmcnt(8)
	s_waitcnt lgkmcnt(0)
	s_barrier
	s_setprio 1
	s_waitcnt lgkmcnt(0)
	v_mfma_f32_16x16x32_bf16 v[62:65], v[162:165], v[194:197], v[62:65]
	v_mfma_f32_16x16x32_bf16 v[58:61], v[170:173], v[194:197], v[58:61]
	v_mfma_f32_16x16x32_bf16 v[54:57], v[162:165], v[202:205], v[54:57]
	v_mfma_f32_16x16x32_bf16 v[46:49], v[170:173], v[202:205], v[46:49]
	v_mfma_f32_16x16x32_bf16 v[38:41], v[162:165], v[232:235], v[38:41]
	v_mfma_f32_16x16x32_bf16 v[30:33], v[170:173], v[232:235], v[30:33]
	v_mfma_f32_16x16x32_bf16 v[22:25], v[162:165], v[240:243], v[22:25]
	v_mfma_f32_16x16x32_bf16 v[14:17], v[170:173], v[240:243], v[14:17]
	v_mfma_f32_16x16x32_bf16 v[62:65], v[166:169], v[198:201], v[62:65]
	v_mfma_f32_16x16x32_bf16 v[58:61], v[174:177], v[198:201], v[58:61]
	v_mfma_f32_16x16x32_bf16 v[54:57], v[166:169], v[206:209], v[54:57]
	v_mfma_f32_16x16x32_bf16 v[46:49], v[174:177], v[206:209], v[46:49]
	v_mfma_f32_16x16x32_bf16 v[38:41], v[166:169], v[236:239], v[38:41]
	v_mfma_f32_16x16x32_bf16 v[30:33], v[174:177], v[236:239], v[30:33]
	v_mfma_f32_16x16x32_bf16 v[22:25], v[166:169], v[244:247], v[22:25]
	v_mfma_f32_16x16x32_bf16 v[14:17], v[174:177], v[244:247], v[14:17]
	v_mfma_f32_16x16x32_bf16 v[50:53], v[178:181], v[194:197], v[50:53]
	v_mfma_f32_16x16x32_bf16 v[42:45], v[186:189], v[194:197], v[42:45]
	v_mfma_f32_16x16x32_bf16 v[34:37], v[178:181], v[202:205], v[34:37]
	v_mfma_f32_16x16x32_bf16 v[26:29], v[186:189], v[202:205], v[26:29]
	v_mfma_f32_16x16x32_bf16 v[18:21], v[178:181], v[232:235], v[18:21]
	v_mfma_f32_16x16x32_bf16 v[10:13], v[186:189], v[232:235], v[10:13]
	v_mfma_f32_16x16x32_bf16 v[6:9], v[178:181], v[240:243], v[6:9]
	v_mfma_f32_16x16x32_bf16 v[2:5], v[186:189], v[240:243], v[2:5]
	v_mfma_f32_16x16x32_bf16 v[50:53], v[182:185], v[198:201], v[50:53]
	v_mfma_f32_16x16x32_bf16 v[42:45], v[190:193], v[198:201], v[42:45]
	v_mfma_f32_16x16x32_bf16 v[34:37], v[182:185], v[206:209], v[34:37]
	v_mfma_f32_16x16x32_bf16 v[26:29], v[190:193], v[206:209], v[26:29]
	v_mfma_f32_16x16x32_bf16 v[18:21], v[182:185], v[236:239], v[18:21]
	v_mfma_f32_16x16x32_bf16 v[10:13], v[190:193], v[236:239], v[10:13]
	v_mfma_f32_16x16x32_bf16 v[6:9], v[182:185], v[244:247], v[6:9]
	v_mfma_f32_16x16x32_bf16 v[2:5], v[190:193], v[244:247], v[2:5]
	s_setprio 0
	s_barrier
	s_add_i32 s75, s75, 2
	s_add_u32 s28, s28, 0x100
	s_addc_u32 s29, s29, 0
	s_add_u32 s73, s73, 0x100
	s_addc_u32 s74, s74, 0
	s_cmp_gt_u32 s75, 13
	s_cbranch_scc0 .LBB0_405
	s_and_b64 vcc, exec, s[16:17]
	s_cbranch_vccz .LBB0_408
	s_barrier

.LBB0_546:
	s_add_u32 s18, s16, 0x100
	s_addc_u32 s19, s17, 0
	s_add_i32 s53, 0, 0x10000
	s_cmp_eq_u32 s52, 2
	s_cselect_b32 s23, s7, s19
	s_cselect_b32 s22, s6, s18
	v_add_u32_e32 v144, s53, v141
	s_cselect_b32 s21, s15, s47
	s_cselect_b32 s20, s14, s46
	s_add_i32 s54, 0, 0x14000
	ds_read_b128 v[162:165], v144
	ds_read_b128 v[166:169], v144 offset:1024
	ds_read_b128 v[170:173], v144 offset:2048
	ds_read_b128 v[174:177], v144 offset:3072
	v_add_u32_e32 v144, s54, v141
	ds_read_b128 v[178:181], v144
	ds_read_b128 v[182:185], v144 offset:1024
	ds_read_b128 v[186:189], v144 offset:2048
	ds_read_b128 v[190:193], v144 offset:3072
	v_lshl_add_u64 v[144:145], s[16:17], 0, v[136:137]
	s_add_i32 m0, s34, 0xc000
	ds_read_b128 v[194:197], v143
	ds_read_b128 v[198:201], v143 offset:1024
	ds_read_b128 v[202:205], v143 offset:2048
	ds_read_b128 v[206:209], v143 offset:3072
	ds_read_b128 v[232:235], v143 offset:4096
	ds_read_b128 v[236:239], v143 offset:5120
	ds_read_b128 v[240:243], v143 offset:6144
	ds_read_b128 v[244:247], v143 offset:7168
	global_load_lds_dwordx4 v[144:145], off
	v_lshl_add_u64 v[144:145], s[16:17], 0, v[138:139]
	s_add_i32 m0, s34, 0xe000
	s_nop 0
	global_load_lds_dwordx4 v[144:145], off
	s_waitcnt vmcnt(8)
	s_waitcnt lgkmcnt(0)
	s_barrier
	s_setprio 1
	s_waitcnt lgkmcnt(0)
	v_mfma_f32_16x16x32_bf16 v[126:129], v[162:165], v[194:197], v[126:129]
	v_mfma_f32_16x16x32_bf16 v[122:125], v[170:173], v[194:197], v[122:125]
	v_mfma_f32_16x16x32_bf16 v[118:121], v[162:165], v[202:205], v[118:121]
	v_mfma_f32_16x16x32_bf16 v[110:113], v[170:173], v[202:205], v[110:113]
	v_mfma_f32_16x16x32_bf16 v[102:105], v[162:165], v[232:235], v[102:105]
	v_mfma_f32_16x16x32_bf16 v[94:97], v[170:173], v[232:235], v[94:97]
	v_mfma_f32_16x16x32_bf16 v[86:89], v[162:165], v[240:243], v[86:89]
	v_mfma_f32_16x16x32_bf16 v[78:81], v[170:173], v[240:243], v[78:81]
	v_mfma_f32_16x16x32_bf16 v[126:129], v[166:169], v[198:201], v[126:129]
	v_mfma_f32_16x16x32_bf16 v[122:125], v[174:177], v[198:201], v[122:125]
	v_mfma_f32_16x16x32_bf16 v[118:121], v[166:169], v[206:209], v[118:121]
	v_mfma_f32_16x16x32_bf16 v[110:113], v[174:177], v[206:209], v[110:113]
	v_mfma_f32_16x16x32_bf16 v[102:105], v[166:169], v[236:239], v[102:105]
	v_mfma_f32_16x16x32_bf16 v[94:97], v[174:177], v[236:239], v[94:97]
	v_mfma_f32_16x16x32_bf16 v[86:89], v[166:169], v[244:247], v[86:89]
	v_mfma_f32_16x16x32_bf16 v[78:81], v[174:177], v[244:247], v[78:81]
	v_mfma_f32_16x16x32_bf16 v[114:117], v[178:181], v[194:197], v[114:117]
	v_mfma_f32_16x16x32_bf16 v[106:109], v[186:189], v[194:197], v[106:109]
	v_mfma_f32_16x16x32_bf16 v[98:101], v[178:181], v[202:205], v[98:101]
	v_mfma_f32_16x16x32_bf16 v[90:93], v[186:189], v[202:205], v[90:93]
	v_mfma_f32_16x16x32_bf16 v[82:85], v[178:181], v[232:235], v[82:85]
	v_mfma_f32_16x16x32_bf16 v[74:77], v[186:189], v[232:235], v[74:77]
	v_mfma_f32_16x16x32_bf16 v[70:73], v[178:181], v[240:243], v[70:73]
	v_mfma_f32_16x16x32_bf16 v[66:69], v[186:189], v[240:243], v[66:69]
	v_mfma_f32_16x16x32_bf16 v[114:117], v[182:185], v[198:201], v[114:117]
	v_mfma_f32_16x16x32_bf16 v[106:109], v[190:193], v[198:201], v[106:109]
	v_mfma_f32_16x16x32_bf16 v[98:101], v[182:185], v[206:209], v[98:101]
	v_mfma_f32_16x16x32_bf16 v[90:93], v[190:193], v[206:209], v[90:93]
	v_mfma_f32_16x16x32_bf16 v[82:85], v[182:185], v[236:239], v[82:85]
	v_mfma_f32_16x16x32_bf16 v[74:77], v[190:193], v[236:239], v[74:77]
	v_mfma_f32_16x16x32_bf16 v[70:73], v[182:185], v[244:247], v[70:73]
	v_mfma_f32_16x16x32_bf16 v[66:69], v[190:193], v[244:247], v[66:69]
	s_setprio 0
	s_barrier
	s_add_i32 s16, s53, s30
	v_lshl_add_u64 v[144:145], s[20:21], 0, v[0:1]
	s_mov_b32 m0, s16
	ds_read_b128 v[194:197], v143 offset:16384
	ds_read_b128 v[198:201], v143 offset:17408
	ds_read_b128 v[202:205], v143 offset:18432
	ds_read_b128 v[206:209], v143 offset:19456
	ds_read_b128 v[232:235], v143 offset:20480
	ds_read_b128 v[236:239], v143 offset:21504
	ds_read_b128 v[240:243], v143 offset:22528
	ds_read_b128 v[244:247], v143 offset:23552
	global_load_lds_dwordx4 v[144:145], off
	s_add_i32 m0, s16, 0x2000
	s_add_u32 s16, s20, 0x18000
	v_lshl_add_u64 v[210:211], s[20:21], 0, v[130:131]
	s_addc_u32 s17, s21, 0
	s_add_i32 s53, s54, s30
	global_load_lds_dwordx4 v[210:211], off
	v_lshl_add_u64 v[220:221], s[16:17], 0, v[0:1]
	s_mov_b32 m0, s53
	v_lshl_add_u64 v[222:223], s[22:23], 0, v[132:133]
	global_load_lds_dwordx4 v[220:221], off
	v_lshl_add_u64 v[220:221], s[16:17], 0, v[130:131]
	s_add_i32 m0, s53, 0x2000
	s_nop 0
	global_load_lds_dwordx4 v[220:221], off
	v_lshl_add_u64 v[220:221], s[22:23], 0, v[134:135]
	s_mov_b32 m0, s34
	s_nop 0
	global_load_lds_dwordx4 v[220:221], off
	s_mov_b32 m0, s35
	s_nop 0
	global_load_lds_dwordx4 v[222:223], off
	s_waitcnt vmcnt(8)
	s_waitcnt lgkmcnt(0)
	s_barrier
	s_setprio 1
	s_waitcnt lgkmcnt(0)
	v_mfma_f32_16x16x32_bf16 v[62:65], v[162:165], v[194:197], v[62:65]
	v_mfma_f32_16x16x32_bf16 v[58:61], v[170:173], v[194:197], v[58:61]
	v_mfma_f32_16x16x32_bf16 v[54:57], v[162:165], v[202:205], v[54:57]
	v_mfma_f32_16x16x32_bf16 v[46:49], v[170:173], v[202:205], v[46:49]
	v_mfma_f32_16x16x32_bf16 v[38:41], v[162:165], v[232:235], v[38:41]
	v_mfma_f32_16x16x32_bf16 v[30:33], v[170:173], v[232:235], v[30:33]
	v_mfma_f32_16x16x32_bf16 v[22:25], v[162:165], v[240:243], v[22:25]
	v_mfma_f32_16x16x32_bf16 v[14:17], v[170:173], v[240:243], v[14:17]
	v_mfma_f32_16x16x32_bf16 v[62:65], v[166:169], v[198:201], v[62:65]
	v_mfma_f32_16x16x32_bf16 v[58:61], v[174:177], v[198:201], v[58:61]
	v_mfma_f32_16x16x32_bf16 v[54:57], v[166:169], v[206:209], v[54:57]
	v_mfma_f32_16x16x32_bf16 v[46:49], v[174:177], v[206:209], v[46:49]
	v_mfma_f32_16x16x32_bf16 v[38:41], v[166:169], v[236:239], v[38:41]
	v_mfma_f32_16x16x32_bf16 v[30:33], v[174:177], v[236:239], v[30:33]
	v_mfma_f32_16x16x32_bf16 v[22:25], v[166:169], v[244:247], v[22:25]
	v_mfma_f32_16x16x32_bf16 v[14:17], v[174:177], v[244:247], v[14:17]
	v_mfma_f32_16x16x32_bf16 v[50:53], v[178:181], v[194:197], v[50:53]
	v_mfma_f32_16x16x32_bf16 v[42:45], v[186:189], v[194:197], v[42:45]
	v_mfma_f32_16x16x32_bf16 v[34:37], v[178:181], v[202:205], v[34:37]
	v_mfma_f32_16x16x32_bf16 v[26:29], v[186:189], v[202:205], v[26:29]
	v_mfma_f32_16x16x32_bf16 v[18:21], v[178:181], v[232:235], v[18:21]
	v_mfma_f32_16x16x32_bf16 v[10:13], v[186:189], v[232:235], v[10:13]
	v_mfma_f32_16x16x32_bf16 v[6:9], v[178:181], v[240:243], v[6:9]
	v_mfma_f32_16x16x32_bf16 v[2:5], v[186:189], v[240:243], v[2:5]
	v_mfma_f32_16x16x32_bf16 v[50:53], v[182:185], v[198:201], v[50:53]
	v_mfma_f32_16x16x32_bf16 v[42:45], v[190:193], v[198:201], v[42:45]
	v_mfma_f32_16x16x32_bf16 v[34:37], v[182:185], v[206:209], v[34:37]
	v_mfma_f32_16x16x32_bf16 v[26:29], v[190:193], v[206:209], v[26:29]
	v_mfma_f32_16x16x32_bf16 v[18:21], v[182:185], v[236:239], v[18:21]
	v_mfma_f32_16x16x32_bf16 v[10:13], v[190:193], v[236:239], v[10:13]
	v_mfma_f32_16x16x32_bf16 v[6:9], v[182:185], v[244:247], v[6:9]
	v_mfma_f32_16x16x32_bf16 v[2:5], v[190:193], v[244:247], v[2:5]
	s_setprio 0
	s_barrier
	s_add_i32 s53, 0, 0x18000
	v_add_u32_e32 v146, s53, v141
	s_add_i32 s54, 0, 0x1c000
	ds_read_b128 v[162:165], v146
	ds_read_b128 v[166:169], v146 offset:1024
	ds_read_b128 v[170:173], v146 offset:2048
	ds_read_b128 v[174:177], v146 offset:3072
	v_add_u32_e32 v146, s54, v141
	ds_read_b128 v[178:181], v146
	ds_read_b128 v[182:185], v146 offset:1024
	ds_read_b128 v[186:189], v146 offset:2048
	ds_read_b128 v[190:193], v146 offset:3072
	s_add_u32 s16, s22, 0x18000
	s_addc_u32 s17, s23, 0
	s_mov_b32 m0, s36
	v_lshl_add_u64 v[248:249], s[16:17], 0, v[134:135]
	ds_read_b128 v[194:197], v143 offset:32768
	ds_read_b128 v[198:201], v143 offset:33792
	ds_read_b128 v[202:205], v143 offset:34816
	ds_read_b128 v[206:209], v143 offset:35840
	ds_read_b128 v[232:235], v143 offset:36864
	ds_read_b128 v[236:239], v143 offset:37888
	ds_read_b128 v[240:243], v143 offset:38912
	ds_read_b128 v[244:247], v143 offset:39936
	global_load_lds_dwordx4 v[248:249], off
	v_lshl_add_u64 v[248:249], s[16:17], 0, v[132:133]
	s_mov_b32 m0, s37
	s_nop 0
	global_load_lds_dwordx4 v[248:249], off
	s_waitcnt vmcnt(8)
	s_waitcnt lgkmcnt(0)
	s_barrier
	s_setprio 1
	s_waitcnt lgkmcnt(0)
	v_mfma_f32_16x16x32_bf16 v[126:129], v[162:165], v[194:197], v[126:129]
	v_mfma_f32_16x16x32_bf16 v[122:125], v[170:173], v[194:197], v[122:125]
	v_mfma_f32_16x16x32_bf16 v[118:121], v[162:165], v[202:205], v[118:121]
	v_mfma_f32_16x16x32_bf16 v[110:113], v[170:173], v[202:205], v[110:113]
	v_mfma_f32_16x16x32_bf16 v[102:105], v[162:165], v[232:235], v[102:105]
	v_mfma_f32_16x16x32_bf16 v[94:97], v[170:173], v[232:235], v[94:97]
	v_mfma_f32_16x16x32_bf16 v[86:89], v[162:165], v[240:243], v[86:89]
	v_mfma_f32_16x16x32_bf16 v[78:81], v[170:173], v[240:243], v[78:81]
	v_mfma_f32_16x16x32_bf16 v[126:129], v[166:169], v[198:201], v[126:129]
	v_mfma_f32_16x16x32_bf16 v[122:125], v[174:177], v[198:201], v[122:125]
	v_mfma_f32_16x16x32_bf16 v[118:121], v[166:169], v[206:209], v[118:121]
	v_mfma_f32_16x16x32_bf16 v[110:113], v[174:177], v[206:209], v[110:113]
	v_mfma_f32_16x16x32_bf16 v[102:105], v[166:169], v[236:239], v[102:105]
	v_mfma_f32_16x16x32_bf16 v[94:97], v[174:177], v[236:239], v[94:97]
	v_mfma_f32_16x16x32_bf16 v[86:89], v[166:169], v[244:247], v[86:89]
	v_mfma_f32_16x16x32_bf16 v[78:81], v[174:177], v[244:247], v[78:81]
	v_mfma_f32_16x16x32_bf16 v[114:117], v[178:181], v[194:197], v[114:117]
	v_mfma_f32_16x16x32_bf16 v[106:109], v[186:189], v[194:197], v[106:109]
	v_mfma_f32_16x16x32_bf16 v[98:101], v[178:181], v[202:205], v[98:101]
	v_mfma_f32_16x16x32_bf16 v[90:93], v[186:189], v[202:205], v[90:93]
	v_mfma_f32_16x16x32_bf16 v[82:85], v[178:181], v[232:235], v[82:85]
	v_mfma_f32_16x16x32_bf16 v[74:77], v[186:189], v[232:235], v[74:77]
	v_mfma_f32_16x16x32_bf16 v[70:73], v[178:181], v[240:243], v[70:73]
	v_mfma_f32_16x16x32_bf16 v[66:69], v[186:189], v[240:243], v[66:69]
	v_mfma_f32_16x16x32_bf16 v[114:117], v[182:185], v[198:201], v[114:117]
	v_mfma_f32_16x16x32_bf16 v[106:109], v[190:193], v[198:201], v[106:109]
	v_mfma_f32_16x16x32_bf16 v[98:101], v[182:185], v[206:209], v[98:101]
	v_mfma_f32_16x16x32_bf16 v[90:93], v[190:193], v[206:209], v[90:93]
	v_mfma_f32_16x16x32_bf16 v[82:85], v[182:185], v[236:239], v[82:85]
	v_mfma_f32_16x16x32_bf16 v[74:77], v[190:193], v[236:239], v[74:77]
	v_mfma_f32_16x16x32_bf16 v[70:73], v[182:185], v[244:247], v[70:73]
	v_mfma_f32_16x16x32_bf16 v[66:69], v[190:193], v[244:247], v[66:69]
	s_setprio 0
	s_barrier
	s_add_i32 s16, s53, s30
	v_lshl_add_u64 v[144:145], v[144:145], 0, s[90:91]
	s_mov_b32 m0, s16
	ds_read_b128 v[194:197], v143 offset:49152
	ds_read_b128 v[198:201], v143 offset:50176
	ds_read_b128 v[202:205], v143 offset:51200
	ds_read_b128 v[206:209], v143 offset:52224
	ds_read_b128 v[232:235], v143 offset:53248
	ds_read_b128 v[236:239], v143 offset:54272
	ds_read_b128 v[240:243], v143 offset:55296
	ds_read_b128 v[244:247], v143 offset:56320
	global_load_lds_dwordx4 v[144:145], off
	s_add_i32 m0, s16, 0x2000
	s_add_u32 s16, s20, 0x18080
	v_lshl_add_u64 v[144:145], v[210:211], 0, s[90:91]
	s_addc_u32 s17, s21, 0
	s_add_i32 s20, s54, s30
	global_load_lds_dwordx4 v[144:145], off
	v_lshl_add_u64 v[144:145], s[16:17], 0, v[0:1]
	s_mov_b32 m0, s20
	s_nop 0
	global_load_lds_dwordx4 v[144:145], off
	v_lshl_add_u64 v[144:145], s[16:17], 0, v[130:131]
	s_add_i32 m0, s20, 0x2000
	s_nop 0
	global_load_lds_dwordx4 v[144:145], off
	v_lshl_add_u64 v[144:145], v[220:221], 0, s[90:91]
	s_mov_b32 m0, s38
	s_nop 0
	global_load_lds_dwordx4 v[144:145], off
	v_lshl_add_u64 v[144:145], v[222:223], 0, s[90:91]
	s_mov_b32 m0, s39
	s_nop 0
	global_load_lds_dwordx4 v[144:145], off
	s_waitcnt vmcnt(8)
	s_waitcnt lgkmcnt(0)
	s_barrier
	s_setprio 1
	s_waitcnt lgkmcnt(0)
	v_mfma_f32_16x16x32_bf16 v[62:65], v[162:165], v[194:197], v[62:65]
	v_mfma_f32_16x16x32_bf16 v[58:61], v[170:173], v[194:197], v[58:61]
	v_mfma_f32_16x16x32_bf16 v[54:57], v[162:165], v[202:205], v[54:57]
	v_mfma_f32_16x16x32_bf16 v[46:49], v[170:173], v[202:205], v[46:49]
	v_mfma_f32_16x16x32_bf16 v[38:41], v[162:165], v[232:235], v[38:41]
	v_mfma_f32_16x16x32_bf16 v[30:33], v[170:173], v[232:235], v[30:33]
	v_mfma_f32_16x16x32_bf16 v[22:25], v[162:165], v[240:243], v[22:25]
	v_mfma_f32_16x16x32_bf16 v[14:17], v[170:173], v[240:243], v[14:17]
	v_mfma_f32_16x16x32_bf16 v[62:65], v[166:169], v[198:201], v[62:65]
	v_mfma_f32_16x16x32_bf16 v[58:61], v[174:177], v[198:201], v[58:61]
	v_mfma_f32_16x16x32_bf16 v[54:57], v[166:169], v[206:209], v[54:57]
	v_mfma_f32_16x16x32_bf16 v[46:49], v[174:177], v[206:209], v[46:49]
	v_mfma_f32_16x16x32_bf16 v[38:41], v[166:169], v[236:239], v[38:41]
	v_mfma_f32_16x16x32_bf16 v[30:33], v[174:177], v[236:239], v[30:33]
	v_mfma_f32_16x16x32_bf16 v[22:25], v[166:169], v[244:247], v[22:25]
	v_mfma_f32_16x16x32_bf16 v[14:17], v[174:177], v[244:247], v[14:17]
	v_mfma_f32_16x16x32_bf16 v[50:53], v[178:181], v[194:197], v[50:53]
	v_mfma_f32_16x16x32_bf16 v[42:45], v[186:189], v[194:197], v[42:45]
	v_mfma_f32_16x16x32_bf16 v[34:37], v[178:181], v[202:205], v[34:37]
	v_mfma_f32_16x16x32_bf16 v[26:29], v[186:189], v[202:205], v[26:29]
	v_mfma_f32_16x16x32_bf16 v[18:21], v[178:181], v[232:235], v[18:21]
	v_mfma_f32_16x16x32_bf16 v[10:13], v[186:189], v[232:235], v[10:13]
	v_mfma_f32_16x16x32_bf16 v[6:9], v[178:181], v[240:243], v[6:9]
	v_mfma_f32_16x16x32_bf16 v[2:5], v[186:189], v[240:243], v[2:5]
	v_mfma_f32_16x16x32_bf16 v[50:53], v[182:185], v[198:201], v[50:53]
	v_mfma_f32_16x16x32_bf16 v[42:45], v[190:193], v[198:201], v[42:45]
	v_mfma_f32_16x16x32_bf16 v[34:37], v[182:185], v[206:209], v[34:37]
	v_mfma_f32_16x16x32_bf16 v[26:29], v[190:193], v[206:209], v[26:29]
	v_mfma_f32_16x16x32_bf16 v[18:21], v[182:185], v[236:239], v[18:21]
	v_mfma_f32_16x16x32_bf16 v[10:13], v[190:193], v[236:239], v[10:13]
	v_mfma_f32_16x16x32_bf16 v[6:9], v[182:185], v[244:247], v[6:9]
	v_mfma_f32_16x16x32_bf16 v[2:5], v[190:193], v[244:247], v[2:5]
	s_setprio 0
	s_barrier
	s_add_i32 s52, s52, 2
	s_add_u32 s46, s46, 0x100
	s_addc_u32 s47, s47, 0
	s_cmp_gt_u32 s52, 3
	s_mov_b64 s[16:17], s[18:19]
	s_cbranch_scc0 .LBB0_546
	s_and_b64 vcc, exec, s[12:13]
	s_cbranch_vccz .LBB0_549
	s_barrier

.LBB0_570:
	s_add_u32 s31, s24, s30
	s_addc_u32 s38, s25, 0
	s_add_u32 s36, s31, 0x100
	s_addc_u32 s37, s38, 0
	s_and_b64 s[34:35], s[28:29], exec
	s_cselect_b32 s35, s15, s37
	s_cselect_b32 s34, s76, s36
	s_add_u32 s30, s22, s30
	s_addc_u32 s36, s23, 0
	s_add_u32 s30, s30, 0x100
	s_addc_u32 s36, s36, 0
	s_add_i32 s56, 0, 0x10000
	s_and_b64 s[28:29], s[28:29], exec
	s_cselect_b32 s37, s13, s36
	s_cselect_b32 s36, s77, s30
	s_add_i32 s29, 0, 0x14000
	s_add_u32 s40, s31, 0x10080
	s_addc_u32 s41, s38, 0
	s_add_i32 vcc_lo, s56, s53
	s_add_i32 m0, s19, 0xc000
	s_add_i32 s57, s19, 0xe000
	s_add_i32 s82, vcc_lo, 0x2000
	v_add_u32_e32 v136, s56, v139
	s_add_u32 s38, s36, 0x10000
	ds_read_b128 v[142:145], v136
	ds_read_b128 v[162:165], v136 offset:1024
	ds_read_b128 v[166:169], v136 offset:2048
	ds_read_b128 v[170:173], v136 offset:3072
	v_add_u32_e32 v136, s29, v139
	s_addc_u32 s39, s37, 0
	s_add_i32 s96, s29, s53
	ds_read_b128 v[174:177], v136
	ds_read_b128 v[178:181], v136 offset:1024
	ds_read_b128 v[182:185], v136 offset:2048
	ds_read_b128 v[186:189], v136 offset:3072
	s_add_i32 s83, s96, 0x2000
	s_add_i32 s81, 0, 0x18000
	s_add_i32 s80, 0, 0x1c000
	s_add_u32 s30, s34, 0x10000
	s_addc_u32 s31, s35, 0
	s_add_i32 s79, s81, s53
	s_add_i32 s78, s79, 0x2000
	s_add_u32 s28, s36, 0x10080
	s_addc_u32 s29, s37, 0
	s_add_i32 vcc_hi, s80, s53
	s_add_i32 s56, vcc_hi, 0x2000
	v_lshl_add_u64 v[136:137], s[40:41], 0, v[130:131]
	ds_read_b128 v[190:193], v141
	ds_read_b128 v[194:197], v141 offset:1024
	ds_read_b128 v[198:201], v141 offset:2048
	ds_read_b128 v[202:205], v141 offset:3072
	ds_read_b128 v[206:209], v141 offset:4096
	ds_read_b128 v[232:235], v141 offset:5120
	ds_read_b128 v[236:239], v141 offset:6144
	ds_read_b128 v[240:243], v141 offset:7168
	global_load_lds_dwordx4 v[136:137], off
	v_lshl_add_u64 v[136:137], s[40:41], 0, v[132:133]
	s_mov_b32 m0, s57
	s_nop 0
	global_load_lds_dwordx4 v[136:137], off
	s_waitcnt vmcnt(8)
	s_waitcnt lgkmcnt(0)
	s_barrier
	s_setprio 1
	s_waitcnt lgkmcnt(0)
	v_mfma_f32_16x16x32_bf16 v[126:129], v[142:145], v[190:193], v[126:129]
	v_mfma_f32_16x16x32_bf16 v[122:125], v[166:169], v[190:193], v[122:125]
	v_mfma_f32_16x16x32_bf16 v[118:121], v[142:145], v[198:201], v[118:121]
	v_mfma_f32_16x16x32_bf16 v[110:113], v[166:169], v[198:201], v[110:113]
	v_mfma_f32_16x16x32_bf16 v[102:105], v[142:145], v[206:209], v[102:105]
	v_mfma_f32_16x16x32_bf16 v[94:97], v[166:169], v[206:209], v[94:97]
	v_mfma_f32_16x16x32_bf16 v[86:89], v[142:145], v[236:239], v[86:89]
	v_mfma_f32_16x16x32_bf16 v[78:81], v[166:169], v[236:239], v[78:81]
	v_mfma_f32_16x16x32_bf16 v[126:129], v[162:165], v[194:197], v[126:129]
	v_mfma_f32_16x16x32_bf16 v[122:125], v[170:173], v[194:197], v[122:125]
	v_mfma_f32_16x16x32_bf16 v[118:121], v[162:165], v[202:205], v[118:121]
	v_mfma_f32_16x16x32_bf16 v[110:113], v[170:173], v[202:205], v[110:113]
	v_mfma_f32_16x16x32_bf16 v[102:105], v[162:165], v[232:235], v[102:105]
	v_mfma_f32_16x16x32_bf16 v[94:97], v[170:173], v[232:235], v[94:97]
	v_mfma_f32_16x16x32_bf16 v[86:89], v[162:165], v[240:243], v[86:89]
	v_mfma_f32_16x16x32_bf16 v[78:81], v[170:173], v[240:243], v[78:81]
	v_mfma_f32_16x16x32_bf16 v[114:117], v[174:177], v[190:193], v[114:117]
	v_mfma_f32_16x16x32_bf16 v[106:109], v[182:185], v[190:193], v[106:109]
	v_mfma_f32_16x16x32_bf16 v[98:101], v[174:177], v[198:201], v[98:101]
	v_mfma_f32_16x16x32_bf16 v[90:93], v[182:185], v[198:201], v[90:93]
	v_mfma_f32_16x16x32_bf16 v[82:85], v[174:177], v[206:209], v[82:85]
	v_mfma_f32_16x16x32_bf16 v[74:77], v[182:185], v[206:209], v[74:77]
	v_mfma_f32_16x16x32_bf16 v[70:73], v[174:177], v[236:239], v[70:73]
	v_mfma_f32_16x16x32_bf16 v[66:69], v[182:185], v[236:239], v[66:69]
	v_mfma_f32_16x16x32_bf16 v[114:117], v[178:181], v[194:197], v[114:117]
	v_mfma_f32_16x16x32_bf16 v[106:109], v[186:189], v[194:197], v[106:109]
	v_mfma_f32_16x16x32_bf16 v[98:101], v[178:181], v[202:205], v[98:101]
	v_mfma_f32_16x16x32_bf16 v[90:93], v[186:189], v[202:205], v[90:93]
	v_mfma_f32_16x16x32_bf16 v[82:85], v[178:181], v[232:235], v[82:85]
	v_mfma_f32_16x16x32_bf16 v[74:77], v[186:189], v[232:235], v[74:77]
	v_mfma_f32_16x16x32_bf16 v[70:73], v[178:181], v[240:243], v[70:73]
	v_mfma_f32_16x16x32_bf16 v[66:69], v[186:189], v[240:243], v[66:69]
	s_setprio 0
	s_barrier
	s_mov_b32 m0, vcc_lo
	v_lshl_add_u64 v[136:137], s[36:37], 0, v[0:1]
	ds_read_b128 v[190:193], v141 offset:16384
	ds_read_b128 v[194:197], v141 offset:17408
	ds_read_b128 v[198:201], v141 offset:18432
	ds_read_b128 v[202:205], v141 offset:19456
	ds_read_b128 v[206:209], v141 offset:20480
	ds_read_b128 v[232:235], v141 offset:21504
	ds_read_b128 v[236:239], v141 offset:22528
	ds_read_b128 v[240:243], v141 offset:23552
	global_load_lds_dwordx4 v[136:137], off
	v_lshl_add_u64 v[210:211], s[36:37], 0, v[134:135]
	s_mov_b32 m0, s82
	v_lshl_add_u64 v[220:221], s[38:39], 0, v[0:1]
	global_load_lds_dwordx4 v[210:211], off
	s_mov_b32 m0, s96
	v_lshl_add_u64 v[222:223], s[34:35], 0, v[132:133]
	global_load_lds_dwordx4 v[220:221], off
	v_lshl_add_u64 v[220:221], s[38:39], 0, v[134:135]
	s_mov_b32 m0, s83
	s_nop 0
	global_load_lds_dwordx4 v[220:221], off
	v_lshl_add_u64 v[220:221], s[34:35], 0, v[130:131]
	s_mov_b32 m0, s19
	s_nop 0
	global_load_lds_dwordx4 v[220:221], off
	s_mov_b32 m0, s54
	s_nop 0
	global_load_lds_dwordx4 v[222:223], off
	s_waitcnt vmcnt(8)
	s_waitcnt lgkmcnt(0)
	s_barrier
	s_setprio 1
	s_waitcnt lgkmcnt(0)
	v_mfma_f32_16x16x32_bf16 v[62:65], v[142:145], v[190:193], v[62:65]
	v_mfma_f32_16x16x32_bf16 v[58:61], v[166:169], v[190:193], v[58:61]
	v_mfma_f32_16x16x32_bf16 v[54:57], v[142:145], v[198:201], v[54:57]
	v_mfma_f32_16x16x32_bf16 v[46:49], v[166:169], v[198:201], v[46:49]
	v_mfma_f32_16x16x32_bf16 v[38:41], v[142:145], v[206:209], v[38:41]
	v_mfma_f32_16x16x32_bf16 v[30:33], v[166:169], v[206:209], v[30:33]
	v_mfma_f32_16x16x32_bf16 v[22:25], v[142:145], v[236:239], v[22:25]
	v_mfma_f32_16x16x32_bf16 v[14:17], v[166:169], v[236:239], v[14:17]
	v_mfma_f32_16x16x32_bf16 v[62:65], v[162:165], v[194:197], v[62:65]
	v_mfma_f32_16x16x32_bf16 v[58:61], v[170:173], v[194:197], v[58:61]
	v_mfma_f32_16x16x32_bf16 v[54:57], v[162:165], v[202:205], v[54:57]
	v_mfma_f32_16x16x32_bf16 v[46:49], v[170:173], v[202:205], v[46:49]
	v_mfma_f32_16x16x32_bf16 v[38:41], v[162:165], v[232:235], v[38:41]
	v_mfma_f32_16x16x32_bf16 v[30:33], v[170:173], v[232:235], v[30:33]
	v_mfma_f32_16x16x32_bf16 v[22:25], v[162:165], v[240:243], v[22:25]
	v_mfma_f32_16x16x32_bf16 v[14:17], v[170:173], v[240:243], v[14:17]
	v_mfma_f32_16x16x32_bf16 v[50:53], v[174:177], v[190:193], v[50:53]
	v_mfma_f32_16x16x32_bf16 v[42:45], v[182:185], v[190:193], v[42:45]
	v_mfma_f32_16x16x32_bf16 v[34:37], v[174:177], v[198:201], v[34:37]
	v_mfma_f32_16x16x32_bf16 v[26:29], v[182:185], v[198:201], v[26:29]
	v_mfma_f32_16x16x32_bf16 v[18:21], v[174:177], v[206:209], v[18:21]
	v_mfma_f32_16x16x32_bf16 v[10:13], v[182:185], v[206:209], v[10:13]
	v_mfma_f32_16x16x32_bf16 v[6:9], v[174:177], v[236:239], v[6:9]
	v_mfma_f32_16x16x32_bf16 v[2:5], v[182:185], v[236:239], v[2:5]
	v_mfma_f32_16x16x32_bf16 v[50:53], v[178:181], v[194:197], v[50:53]
	v_mfma_f32_16x16x32_bf16 v[42:45], v[186:189], v[194:197], v[42:45]
	v_mfma_f32_16x16x32_bf16 v[34:37], v[178:181], v[202:205], v[34:37]
	v_mfma_f32_16x16x32_bf16 v[26:29], v[186:189], v[202:205], v[26:29]
	v_mfma_f32_16x16x32_bf16 v[18:21], v[178:181], v[232:235], v[18:21]
	v_mfma_f32_16x16x32_bf16 v[10:13], v[186:189], v[232:235], v[10:13]
	v_mfma_f32_16x16x32_bf16 v[6:9], v[178:181], v[240:243], v[6:9]
	v_mfma_f32_16x16x32_bf16 v[2:5], v[186:189], v[240:243], v[2:5]
	s_setprio 0
	s_barrier
	v_add_u32_e32 v146, s81, v139
	ds_read_b128 v[142:145], v146
	ds_read_b128 v[162:165], v146 offset:1024
	ds_read_b128 v[166:169], v146 offset:2048
	ds_read_b128 v[170:173], v146 offset:3072
	v_add_u32_e32 v146, s80, v139
	ds_read_b128 v[174:177], v146
	ds_read_b128 v[178:181], v146 offset:1024
	ds_read_b128 v[182:185], v146 offset:2048
	ds_read_b128 v[186:189], v146 offset:3072
	s_mov_b32 m0, s55
	v_lshl_add_u64 v[244:245], s[30:31], 0, v[130:131]
	ds_read_b128 v[190:193], v141 offset:32768
	ds_read_b128 v[194:197], v141 offset:33792
	ds_read_b128 v[198:201], v141 offset:34816
	ds_read_b128 v[202:205], v141 offset:35840
	ds_read_b128 v[206:209], v141 offset:36864
	ds_read_b128 v[232:235], v141 offset:37888
	ds_read_b128 v[236:239], v141 offset:38912
	ds_read_b128 v[240:243], v141 offset:39936
	global_load_lds_dwordx4 v[244:245], off
	v_lshl_add_u64 v[244:245], s[30:31], 0, v[132:133]
	s_mov_b32 m0, s70
	s_nop 0
	global_load_lds_dwordx4 v[244:245], off
	s_waitcnt vmcnt(8)
	s_waitcnt lgkmcnt(0)
	s_barrier
	s_setprio 1
	s_waitcnt lgkmcnt(0)
	v_mfma_f32_16x16x32_bf16 v[126:129], v[142:145], v[190:193], v[126:129]
	v_mfma_f32_16x16x32_bf16 v[122:125], v[166:169], v[190:193], v[122:125]
	v_mfma_f32_16x16x32_bf16 v[118:121], v[142:145], v[198:201], v[118:121]
	v_mfma_f32_16x16x32_bf16 v[110:113], v[166:169], v[198:201], v[110:113]
	v_mfma_f32_16x16x32_bf16 v[102:105], v[142:145], v[206:209], v[102:105]
	v_mfma_f32_16x16x32_bf16 v[94:97], v[166:169], v[206:209], v[94:97]
	v_mfma_f32_16x16x32_bf16 v[86:89], v[142:145], v[236:239], v[86:89]
	v_mfma_f32_16x16x32_bf16 v[78:81], v[166:169], v[236:239], v[78:81]
	v_mfma_f32_16x16x32_bf16 v[126:129], v[162:165], v[194:197], v[126:129]
	v_mfma_f32_16x16x32_bf16 v[122:125], v[170:173], v[194:197], v[122:125]
	v_mfma_f32_16x16x32_bf16 v[118:121], v[162:165], v[202:205], v[118:121]
	v_mfma_f32_16x16x32_bf16 v[110:113], v[170:173], v[202:205], v[110:113]
	v_mfma_f32_16x16x32_bf16 v[102:105], v[162:165], v[232:235], v[102:105]
	v_mfma_f32_16x16x32_bf16 v[94:97], v[170:173], v[232:235], v[94:97]
	v_mfma_f32_16x16x32_bf16 v[86:89], v[162:165], v[240:243], v[86:89]
	v_mfma_f32_16x16x32_bf16 v[78:81], v[170:173], v[240:243], v[78:81]
	v_mfma_f32_16x16x32_bf16 v[114:117], v[174:177], v[190:193], v[114:117]
	v_mfma_f32_16x16x32_bf16 v[106:109], v[182:185], v[190:193], v[106:109]
	v_mfma_f32_16x16x32_bf16 v[98:101], v[174:177], v[198:201], v[98:101]
	v_mfma_f32_16x16x32_bf16 v[90:93], v[182:185], v[198:201], v[90:93]
	v_mfma_f32_16x16x32_bf16 v[82:85], v[174:177], v[206:209], v[82:85]
	v_mfma_f32_16x16x32_bf16 v[74:77], v[182:185], v[206:209], v[74:77]
	v_mfma_f32_16x16x32_bf16 v[70:73], v[174:177], v[236:239], v[70:73]
	v_mfma_f32_16x16x32_bf16 v[66:69], v[182:185], v[236:239], v[66:69]
	v_mfma_f32_16x16x32_bf16 v[114:117], v[178:181], v[194:197], v[114:117]
	v_mfma_f32_16x16x32_bf16 v[106:109], v[186:189], v[194:197], v[106:109]
	v_mfma_f32_16x16x32_bf16 v[98:101], v[178:181], v[202:205], v[98:101]
	v_mfma_f32_16x16x32_bf16 v[90:93], v[186:189], v[202:205], v[90:93]
	v_mfma_f32_16x16x32_bf16 v[82:85], v[178:181], v[232:235], v[82:85]
	v_mfma_f32_16x16x32_bf16 v[74:77], v[186:189], v[232:235], v[74:77]
	v_mfma_f32_16x16x32_bf16 v[70:73], v[178:181], v[240:243], v[70:73]
	v_mfma_f32_16x16x32_bf16 v[66:69], v[186:189], v[240:243], v[66:69]
	s_setprio 0
	s_barrier
	s_mov_b32 m0, s79
	v_lshl_add_u64 v[136:137], v[136:137], 0, s[90:91]
	ds_read_b128 v[190:193], v141 offset:49152
	ds_read_b128 v[194:197], v141 offset:50176
	ds_read_b128 v[198:201], v141 offset:51200
	ds_read_b128 v[202:205], v141 offset:52224
	ds_read_b128 v[206:209], v141 offset:53248
	ds_read_b128 v[232:235], v141 offset:54272
	ds_read_b128 v[236:239], v141 offset:55296
	ds_read_b128 v[240:243], v141 offset:56320
	global_load_lds_dwordx4 v[136:137], off
	v_lshl_add_u64 v[136:137], v[210:211], 0, s[90:91]
	s_mov_b32 m0, s78
	s_nop 0
	global_load_lds_dwordx4 v[136:137], off
	v_lshl_add_u64 v[136:137], s[28:29], 0, v[0:1]
	s_mov_b32 m0, vcc_hi
	s_nop 0
	global_load_lds_dwordx4 v[136:137], off
	v_lshl_add_u64 v[136:137], s[28:29], 0, v[134:135]
	s_mov_b32 m0, s56
	s_nop 0
	global_load_lds_dwordx4 v[136:137], off
	v_lshl_add_u64 v[136:137], v[220:221], 0, s[90:91]
	s_mov_b32 m0, s71
	s_nop 0
	global_load_lds_dwordx4 v[136:137], off
	v_lshl_add_u64 v[136:137], v[222:223], 0, s[90:91]
	s_mov_b32 m0, s72
	s_nop 0
	global_load_lds_dwordx4 v[136:137], off
	s_waitcnt vmcnt(8)
	s_waitcnt lgkmcnt(0)
	s_barrier
	s_setprio 1
	s_waitcnt lgkmcnt(0)
	v_mfma_f32_16x16x32_bf16 v[62:65], v[142:145], v[190:193], v[62:65]
	v_mfma_f32_16x16x32_bf16 v[58:61], v[166:169], v[190:193], v[58:61]
	v_mfma_f32_16x16x32_bf16 v[54:57], v[142:145], v[198:201], v[54:57]
	v_mfma_f32_16x16x32_bf16 v[46:49], v[166:169], v[198:201], v[46:49]
	v_mfma_f32_16x16x32_bf16 v[38:41], v[142:145], v[206:209], v[38:41]
	v_mfma_f32_16x16x32_bf16 v[30:33], v[166:169], v[206:209], v[30:33]
	v_mfma_f32_16x16x32_bf16 v[22:25], v[142:145], v[236:239], v[22:25]
	v_mfma_f32_16x16x32_bf16 v[14:17], v[166:169], v[236:239], v[14:17]
	v_mfma_f32_16x16x32_bf16 v[62:65], v[162:165], v[194:197], v[62:65]
	v_mfma_f32_16x16x32_bf16 v[58:61], v[170:173], v[194:197], v[58:61]
	v_mfma_f32_16x16x32_bf16 v[54:57], v[162:165], v[202:205], v[54:57]
	v_mfma_f32_16x16x32_bf16 v[46:49], v[170:173], v[202:205], v[46:49]
	v_mfma_f32_16x16x32_bf16 v[38:41], v[162:165], v[232:235], v[38:41]
	v_mfma_f32_16x16x32_bf16 v[30:33], v[170:173], v[232:235], v[30:33]
	v_mfma_f32_16x16x32_bf16 v[22:25], v[162:165], v[240:243], v[22:25]
	v_mfma_f32_16x16x32_bf16 v[14:17], v[170:173], v[240:243], v[14:17]
	v_mfma_f32_16x16x32_bf16 v[50:53], v[174:177], v[190:193], v[50:53]
	v_mfma_f32_16x16x32_bf16 v[42:45], v[182:185], v[190:193], v[42:45]
	v_mfma_f32_16x16x32_bf16 v[34:37], v[174:177], v[198:201], v[34:37]
	v_mfma_f32_16x16x32_bf16 v[26:29], v[182:185], v[198:201], v[26:29]
	v_mfma_f32_16x16x32_bf16 v[18:21], v[174:177], v[206:209], v[18:21]
	v_mfma_f32_16x16x32_bf16 v[10:13], v[182:185], v[206:209], v[10:13]
	v_mfma_f32_16x16x32_bf16 v[6:9], v[174:177], v[236:239], v[6:9]
	v_mfma_f32_16x16x32_bf16 v[2:5], v[182:185], v[236:239], v[2:5]
	v_mfma_f32_16x16x32_bf16 v[50:53], v[178:181], v[194:197], v[50:53]
	v_mfma_f32_16x16x32_bf16 v[42:45], v[186:189], v[194:197], v[42:45]
	v_mfma_f32_16x16x32_bf16 v[34:37], v[178:181], v[202:205], v[34:37]
	v_mfma_f32_16x16x32_bf16 v[26:29], v[186:189], v[202:205], v[26:29]
	v_mfma_f32_16x16x32_bf16 v[18:21], v[178:181], v[232:235], v[18:21]
	v_mfma_f32_16x16x32_bf16 v[10:13], v[186:189], v[232:235], v[10:13]
	v_mfma_f32_16x16x32_bf16 v[6:9], v[178:181], v[240:243], v[6:9]
	v_mfma_f32_16x16x32_bf16 v[2:5], v[186:189], v[240:243], v[2:5]
	s_setprio 0
	s_barrier
	s_movk_i32 s30, 0x100
	s_andn2_b64 vcc, exec, s[26:27]
	s_mov_b64 s[28:29], -1
	s_mov_b64 s[26:27], 0
	s_cbranch_vccz .LBB0_570
	s_and_b64 vcc, exec, s[10:11]
	s_cbranch_vccz .LBB0_573
	s_barrier

.LBB0_586:
	s_ashr_i32 s13, s12, 31
	s_lshl_b64 s[16:17], s[12:13], 17
	s_add_u32 s16, s30, s16
	v_cmp_lt_i64_e32 vcc, s[6:7], v[152:153]
	s_addc_u32 s17, s31, s17
	s_and_b64 s[18:19], vcc, exec
	s_cselect_b32 s27, s17, s21
	s_cselect_b32 s26, s16, s20
	s_ashr_i32 s11, s10, 31
	s_lshl_b64 s[18:19], s[10:11], 17
	s_add_u32 s18, s34, s18
	s_addc_u32 s19, s35, s19
	s_and_b64 s[24:25], vcc, exec
	s_cselect_b32 s25, s19, s23
	s_cselect_b32 s24, s18, s22
	s_add_i32 s13, 0, 0x10000
	s_add_i32 s45, 0, 0x14000
	v_add_u32_e32 v146, s13, v43
	v_add_u32_e32 v160, s45, v43
	ds_read_b128 v[2:5], v146
	ds_read_b128 v[6:9], v146 offset:1024
	ds_read_b128 v[10:13], v146 offset:2048
	ds_read_b128 v[14:17], v146 offset:3072
	ds_read_b128 v[18:21], v160
	ds_read_b128 v[22:25], v160 offset:1024
	ds_read_b128 v[26:29], v160 offset:2048
	ds_read_b128 v[30:33], v160 offset:3072
	s_add_u32 s46, s20, 0x10080
	s_addc_u32 s47, s21, 0
	s_add_i32 s53, s15, 0xc000
	v_lshl_add_u64 v[40:41], s[46:47], 0, v[34:35]
	s_mov_b32 m0, s53
	s_add_i32 s11, s15, 0xe000
	ds_read_b128 v[46:49], v45
	ds_read_b128 v[50:53], v45 offset:1024
	ds_read_b128 v[54:57], v45 offset:2048
	ds_read_b128 v[58:61], v45 offset:3072
	ds_read_b128 v[62:65], v45 offset:4096
	ds_read_b128 v[66:69], v45 offset:5120
	ds_read_b128 v[70:73], v45 offset:6144
	ds_read_b128 v[74:77], v45 offset:7168
	global_load_lds_dwordx4 v[40:41], off
	v_lshl_add_u64 v[40:41], s[46:47], 0, v[36:37]
	s_mov_b32 m0, s11
	s_nop 0
	global_load_lds_dwordx4 v[40:41], off
	s_waitcnt vmcnt(8)
	s_waitcnt lgkmcnt(0)
	s_barrier
	s_setprio 1
	s_waitcnt lgkmcnt(0)
	v_mfma_f32_16x16x32_bf16 v[78:81], v[2:5], v[46:49], 0
	v_mfma_f32_16x16x32_bf16 v[82:85], v[10:13], v[46:49], 0
	v_mfma_f32_16x16x32_bf16 v[86:89], v[2:5], v[54:57], 0
	v_mfma_f32_16x16x32_bf16 v[90:93], v[10:13], v[54:57], 0
	v_mfma_f32_16x16x32_bf16 v[94:97], v[2:5], v[62:65], 0
	v_mfma_f32_16x16x32_bf16 v[98:101], v[10:13], v[62:65], 0
	v_mfma_f32_16x16x32_bf16 v[102:105], v[2:5], v[70:73], 0
	v_mfma_f32_16x16x32_bf16 v[106:109], v[10:13], v[70:73], 0
	v_mfma_f32_16x16x32_bf16 v[78:81], v[6:9], v[50:53], v[78:81]
	v_mfma_f32_16x16x32_bf16 v[82:85], v[14:17], v[50:53], v[82:85]
	v_mfma_f32_16x16x32_bf16 v[86:89], v[6:9], v[58:61], v[86:89]
	v_mfma_f32_16x16x32_bf16 v[90:93], v[14:17], v[58:61], v[90:93]
	v_mfma_f32_16x16x32_bf16 v[94:97], v[6:9], v[66:69], v[94:97]
	v_mfma_f32_16x16x32_bf16 v[98:101], v[14:17], v[66:69], v[98:101]
	v_mfma_f32_16x16x32_bf16 v[102:105], v[6:9], v[74:77], v[102:105]
	v_mfma_f32_16x16x32_bf16 v[106:109], v[14:17], v[74:77], v[106:109]
	v_mfma_f32_16x16x32_bf16 v[110:113], v[18:21], v[46:49], 0
	v_mfma_f32_16x16x32_bf16 v[46:49], v[26:29], v[46:49], 0
	v_mfma_f32_16x16x32_bf16 v[110:113], v[22:25], v[50:53], v[110:113]
	v_mfma_f32_16x16x32_bf16 v[46:49], v[30:33], v[50:53], v[46:49]
	v_mfma_f32_16x16x32_bf16 v[50:53], v[18:21], v[54:57], 0
	v_mfma_f32_16x16x32_bf16 v[54:57], v[26:29], v[54:57], 0
	v_mfma_f32_16x16x32_bf16 v[50:53], v[22:25], v[58:61], v[50:53]
	v_mfma_f32_16x16x32_bf16 v[54:57], v[30:33], v[58:61], v[54:57]
	v_mfma_f32_16x16x32_bf16 v[58:61], v[18:21], v[62:65], 0
	v_mfma_f32_16x16x32_bf16 v[62:65], v[26:29], v[62:65], 0
	v_mfma_f32_16x16x32_bf16 v[58:61], v[22:25], v[66:69], v[58:61]
	v_mfma_f32_16x16x32_bf16 v[62:65], v[30:33], v[66:69], v[62:65]
	v_mfma_f32_16x16x32_bf16 v[66:69], v[18:21], v[70:73], 0
	v_mfma_f32_16x16x32_bf16 v[70:73], v[26:29], v[70:73], 0
	v_mfma_f32_16x16x32_bf16 v[66:69], v[22:25], v[74:77], v[66:69]
	v_mfma_f32_16x16x32_bf16 v[70:73], v[30:33], v[74:77], v[70:73]
	s_setprio 0
	s_barrier
	s_add_i32 s47, s13, s36
	v_lshl_add_u64 v[40:41], s[22:23], 0, v[0:1]
	s_mov_b64 s[56:57], 0x100
	s_add_i32 s13, s47, 0x2000
	v_lshl_add_u64 v[142:143], v[40:41], 0, s[56:57]
	s_mov_b32 m0, s47
	v_lshl_add_u64 v[210:211], s[22:23], 0, v[38:39]
	s_add_u32 s54, s22, 0x10100
	ds_read_b128 v[74:77], v45 offset:16384
	ds_read_b128 v[114:117], v45 offset:17408
	ds_read_b128 v[118:121], v45 offset:18432
	ds_read_b128 v[122:125], v45 offset:19456
	ds_read_b128 v[126:129], v45 offset:20480
	ds_read_b128 v[130:133], v45 offset:21504
	ds_read_b128 v[134:137], v45 offset:22528
	ds_read_b128 v[138:141], v45 offset:23552
	global_load_lds_dwordx4 v[142:143], off
	v_lshl_add_u64 v[142:143], v[210:211], 0, s[56:57]
	s_mov_b32 m0, s13
	s_addc_u32 s55, s23, 0
	s_add_i32 s45, s45, s36
	global_load_lds_dwordx4 v[142:143], off
	v_lshl_add_u64 v[142:143], s[54:55], 0, v[0:1]
	s_mov_b32 m0, s45
	s_add_i32 s46, s45, 0x2000
	global_load_lds_dwordx4 v[142:143], off
	v_lshl_add_u64 v[142:143], s[54:55], 0, v[38:39]
	s_mov_b32 m0, s46
	v_lshl_add_u64 v[220:221], s[20:21], 0, v[34:35]
	global_load_lds_dwordx4 v[142:143], off
	v_lshl_add_u64 v[142:143], v[220:221], 0, s[56:57]
	s_mov_b32 m0, s15
	v_lshl_add_u64 v[222:223], s[20:21], 0, v[36:37]
	global_load_lds_dwordx4 v[142:143], off
	v_lshl_add_u64 v[142:143], v[222:223], 0, s[56:57]
	s_mov_b32 m0, s37
	s_nop 0
	global_load_lds_dwordx4 v[142:143], off
	s_waitcnt vmcnt(8)
	s_waitcnt lgkmcnt(0)
	s_barrier
	s_setprio 1
	s_waitcnt lgkmcnt(0)
	v_mfma_f32_16x16x32_bf16 v[142:145], v[2:5], v[74:77], 0
	v_mfma_f32_16x16x32_bf16 v[166:169], v[2:5], v[118:121], 0
	v_mfma_f32_16x16x32_bf16 v[174:177], v[2:5], v[126:129], 0
	v_mfma_f32_16x16x32_bf16 v[2:5], v[2:5], v[134:137], 0
	v_mfma_f32_16x16x32_bf16 v[142:145], v[6:9], v[114:117], v[142:145]
	v_mfma_f32_16x16x32_bf16 v[162:165], v[10:13], v[74:77], 0
	v_mfma_f32_16x16x32_bf16 v[166:169], v[6:9], v[122:125], v[166:169]
	v_mfma_f32_16x16x32_bf16 v[170:173], v[10:13], v[118:121], 0
	v_mfma_f32_16x16x32_bf16 v[174:177], v[6:9], v[130:133], v[174:177]
	v_mfma_f32_16x16x32_bf16 v[178:181], v[10:13], v[126:129], 0
	v_mfma_f32_16x16x32_bf16 v[2:5], v[6:9], v[138:141], v[2:5]
	v_mfma_f32_16x16x32_bf16 v[6:9], v[10:13], v[134:137], 0
	v_mfma_f32_16x16x32_bf16 v[162:165], v[14:17], v[114:117], v[162:165]
	v_mfma_f32_16x16x32_bf16 v[170:173], v[14:17], v[122:125], v[170:173]
	v_mfma_f32_16x16x32_bf16 v[178:181], v[14:17], v[130:133], v[178:181]
	v_mfma_f32_16x16x32_bf16 v[6:9], v[14:17], v[138:141], v[6:9]
	v_mfma_f32_16x16x32_bf16 v[10:13], v[18:21], v[74:77], 0
	v_mfma_f32_16x16x32_bf16 v[14:17], v[26:29], v[74:77], 0
	v_mfma_f32_16x16x32_bf16 v[10:13], v[22:25], v[114:117], v[10:13]
	v_mfma_f32_16x16x32_bf16 v[14:17], v[30:33], v[114:117], v[14:17]
	v_mfma_f32_16x16x32_bf16 v[74:77], v[18:21], v[118:121], 0
	v_mfma_f32_16x16x32_bf16 v[114:117], v[26:29], v[118:121], 0
	v_mfma_f32_16x16x32_bf16 v[118:121], v[18:21], v[126:129], 0
	v_mfma_f32_16x16x32_bf16 v[18:21], v[18:21], v[134:137], 0
	v_mfma_f32_16x16x32_bf16 v[74:77], v[22:25], v[122:125], v[74:77]
	v_mfma_f32_16x16x32_bf16 v[114:117], v[30:33], v[122:125], v[114:117]
	v_mfma_f32_16x16x32_bf16 v[118:121], v[22:25], v[130:133], v[118:121]
	v_mfma_f32_16x16x32_bf16 v[122:125], v[26:29], v[126:129], 0
	v_mfma_f32_16x16x32_bf16 v[18:21], v[22:25], v[138:141], v[18:21]
	v_mfma_f32_16x16x32_bf16 v[22:25], v[26:29], v[134:137], 0
	v_mfma_f32_16x16x32_bf16 v[122:125], v[30:33], v[130:133], v[122:125]
	v_mfma_f32_16x16x32_bf16 v[22:25], v[30:33], v[138:141], v[22:25]
	s_setprio 0
	s_barrier
	s_add_i32 s52, 0, 0x18000
	s_add_i32 s70, 0, 0x1c000
	v_add_u32_e32 v231, s52, v43
	v_add_u32_e32 v246, s70, v43
	ds_read_b128 v[26:29], v231
	ds_read_b128 v[30:33], v231 offset:1024
	ds_read_b128 v[126:129], v231 offset:2048
	ds_read_b128 v[130:133], v231 offset:3072
	ds_read_b128 v[134:137], v246
	ds_read_b128 v[138:141], v246 offset:1024
	ds_read_b128 v[182:185], v246 offset:2048
	ds_read_b128 v[186:189], v246 offset:3072
	s_add_u32 s54, s20, 0x10100
	s_addc_u32 s55, s21, 0
	s_mov_b32 m0, s38
	v_lshl_add_u64 v[244:245], s[54:55], 0, v[34:35]
	ds_read_b128 v[190:193], v45 offset:32768
	ds_read_b128 v[194:197], v45 offset:33792
	ds_read_b128 v[198:201], v45 offset:34816
	ds_read_b128 v[202:205], v45 offset:35840
	ds_read_b128 v[206:209], v45 offset:36864
	ds_read_b128 v[232:235], v45 offset:37888
	ds_read_b128 v[236:239], v45 offset:38912
	ds_read_b128 v[240:243], v45 offset:39936
	global_load_lds_dwordx4 v[244:245], off
	v_lshl_add_u64 v[244:245], s[54:55], 0, v[36:37]
	s_mov_b32 m0, s39
	s_nop 0
	global_load_lds_dwordx4 v[244:245], off
	s_waitcnt vmcnt(8)
	s_waitcnt lgkmcnt(0)
	s_barrier
	s_setprio 1
	s_waitcnt lgkmcnt(0)
	v_mfma_f32_16x16x32_bf16 v[78:81], v[26:29], v[190:193], v[78:81]
	v_mfma_f32_16x16x32_bf16 v[82:85], v[126:129], v[190:193], v[82:85]
	v_mfma_f32_16x16x32_bf16 v[86:89], v[26:29], v[198:201], v[86:89]
	v_mfma_f32_16x16x32_bf16 v[90:93], v[126:129], v[198:201], v[90:93]
	v_mfma_f32_16x16x32_bf16 v[94:97], v[26:29], v[206:209], v[94:97]
	v_mfma_f32_16x16x32_bf16 v[98:101], v[126:129], v[206:209], v[98:101]
	v_mfma_f32_16x16x32_bf16 v[102:105], v[26:29], v[236:239], v[102:105]
	v_mfma_f32_16x16x32_bf16 v[106:109], v[126:129], v[236:239], v[106:109]
	v_mfma_f32_16x16x32_bf16 v[78:81], v[30:33], v[194:197], v[78:81]
	v_mfma_f32_16x16x32_bf16 v[82:85], v[130:133], v[194:197], v[82:85]
	v_mfma_f32_16x16x32_bf16 v[86:89], v[30:33], v[202:205], v[86:89]
	v_mfma_f32_16x16x32_bf16 v[90:93], v[130:133], v[202:205], v[90:93]
	v_mfma_f32_16x16x32_bf16 v[94:97], v[30:33], v[232:235], v[94:97]
	v_mfma_f32_16x16x32_bf16 v[98:101], v[130:133], v[232:235], v[98:101]
	v_mfma_f32_16x16x32_bf16 v[102:105], v[30:33], v[240:243], v[102:105]
	v_mfma_f32_16x16x32_bf16 v[106:109], v[130:133], v[240:243], v[106:109]
	v_mfma_f32_16x16x32_bf16 v[110:113], v[134:137], v[190:193], v[110:113]
	v_mfma_f32_16x16x32_bf16 v[46:49], v[182:185], v[190:193], v[46:49]
	v_mfma_f32_16x16x32_bf16 v[50:53], v[134:137], v[198:201], v[50:53]
	v_mfma_f32_16x16x32_bf16 v[54:57], v[182:185], v[198:201], v[54:57]
	v_mfma_f32_16x16x32_bf16 v[58:61], v[134:137], v[206:209], v[58:61]
	v_mfma_f32_16x16x32_bf16 v[62:65], v[182:185], v[206:209], v[62:65]
	v_mfma_f32_16x16x32_bf16 v[66:69], v[134:137], v[236:239], v[66:69]
	v_mfma_f32_16x16x32_bf16 v[70:73], v[182:185], v[236:239], v[70:73]
	v_mfma_f32_16x16x32_bf16 v[110:113], v[138:141], v[194:197], v[110:113]
	v_mfma_f32_16x16x32_bf16 v[46:49], v[186:189], v[194:197], v[46:49]
	v_mfma_f32_16x16x32_bf16 v[50:53], v[138:141], v[202:205], v[50:53]
	v_mfma_f32_16x16x32_bf16 v[54:57], v[186:189], v[202:205], v[54:57]
	v_mfma_f32_16x16x32_bf16 v[58:61], v[138:141], v[232:235], v[58:61]
	v_mfma_f32_16x16x32_bf16 v[62:65], v[186:189], v[232:235], v[62:65]
	v_mfma_f32_16x16x32_bf16 v[66:69], v[138:141], v[240:243], v[66:69]
	v_mfma_f32_16x16x32_bf16 v[70:73], v[186:189], v[240:243], v[70:73]
	s_setprio 0
	s_barrier
	s_add_i32 s54, s52, s36
	s_mov_b64 s[76:77], 0x180
	s_add_i32 s52, s54, 0x2000
	v_lshl_add_u64 v[40:41], v[40:41], 0, s[76:77]
	s_mov_b32 m0, s54
	s_add_u32 s56, s22, 0x10180
	ds_read_b128 v[190:193], v45 offset:49152
	ds_read_b128 v[194:197], v45 offset:50176
	ds_read_b128 v[198:201], v45 offset:51200
	ds_read_b128 v[202:205], v45 offset:52224
	ds_read_b128 v[206:209], v45 offset:53248
	ds_read_b128 v[232:235], v45 offset:54272
	ds_read_b128 v[236:239], v45 offset:55296
	ds_read_b128 v[240:243], v45 offset:56320
	global_load_lds_dwordx4 v[40:41], off
	v_lshl_add_u64 v[40:41], v[210:211], 0, s[76:77]
	s_mov_b32 m0, s52
	s_addc_u32 s57, s23, 0
	s_add_i32 s22, s70, s36
	global_load_lds_dwordx4 v[40:41], off
	v_lshl_add_u64 v[40:41], s[56:57], 0, v[0:1]
	s_mov_b32 m0, s22
	s_add_i32 s23, s22, 0x2000
	global_load_lds_dwordx4 v[40:41], off
	v_lshl_add_u64 v[40:41], s[56:57], 0, v[38:39]
	s_mov_b32 m0, s23
	s_nop 0
	global_load_lds_dwordx4 v[40:41], off
	v_lshl_add_u64 v[40:41], v[220:221], 0, s[76:77]
	s_mov_b32 m0, s40
	s_nop 0
	global_load_lds_dwordx4 v[40:41], off
	v_lshl_add_u64 v[40:41], v[222:223], 0, s[76:77]
	s_mov_b32 m0, s41
	s_nop 0
	global_load_lds_dwordx4 v[40:41], off
	s_waitcnt vmcnt(8)
	s_waitcnt lgkmcnt(0)
	s_barrier
	s_setprio 1
	s_waitcnt lgkmcnt(0)
	v_mfma_f32_16x16x32_bf16 v[142:145], v[26:29], v[190:193], v[142:145]
	v_mfma_f32_16x16x32_bf16 v[162:165], v[126:129], v[190:193], v[162:165]
	v_mfma_f32_16x16x32_bf16 v[166:169], v[26:29], v[198:201], v[166:169]
	v_mfma_f32_16x16x32_bf16 v[170:173], v[126:129], v[198:201], v[170:173]
	v_mfma_f32_16x16x32_bf16 v[174:177], v[26:29], v[206:209], v[174:177]
	v_mfma_f32_16x16x32_bf16 v[178:181], v[126:129], v[206:209], v[178:181]
	v_mfma_f32_16x16x32_bf16 v[2:5], v[26:29], v[236:239], v[2:5]
	v_mfma_f32_16x16x32_bf16 v[6:9], v[126:129], v[236:239], v[6:9]
	v_mfma_f32_16x16x32_bf16 v[142:145], v[30:33], v[194:197], v[142:145]
	v_mfma_f32_16x16x32_bf16 v[162:165], v[130:133], v[194:197], v[162:165]
	v_mfma_f32_16x16x32_bf16 v[166:169], v[30:33], v[202:205], v[166:169]
	v_mfma_f32_16x16x32_bf16 v[170:173], v[130:133], v[202:205], v[170:173]
	v_mfma_f32_16x16x32_bf16 v[174:177], v[30:33], v[232:235], v[174:177]
	v_mfma_f32_16x16x32_bf16 v[178:181], v[130:133], v[232:235], v[178:181]
	v_mfma_f32_16x16x32_bf16 v[2:5], v[30:33], v[240:243], v[2:5]
	v_mfma_f32_16x16x32_bf16 v[6:9], v[130:133], v[240:243], v[6:9]
	v_mfma_f32_16x16x32_bf16 v[10:13], v[134:137], v[190:193], v[10:13]
	v_mfma_f32_16x16x32_bf16 v[14:17], v[182:185], v[190:193], v[14:17]
	v_mfma_f32_16x16x32_bf16 v[26:29], v[134:137], v[198:201], v[74:77]
	v_mfma_f32_16x16x32_bf16 v[30:33], v[182:185], v[198:201], v[114:117]
	v_mfma_f32_16x16x32_bf16 v[74:77], v[134:137], v[206:209], v[118:121]
	v_mfma_f32_16x16x32_bf16 v[114:117], v[182:185], v[206:209], v[122:125]
	v_mfma_f32_16x16x32_bf16 v[18:21], v[134:137], v[236:239], v[18:21]
	v_mfma_f32_16x16x32_bf16 v[22:25], v[182:185], v[236:239], v[22:25]
	v_mfma_f32_16x16x32_bf16 v[10:13], v[138:141], v[194:197], v[10:13]
	v_mfma_f32_16x16x32_bf16 v[14:17], v[186:189], v[194:197], v[14:17]
	v_mfma_f32_16x16x32_bf16 v[26:29], v[138:141], v[202:205], v[26:29]
	v_mfma_f32_16x16x32_bf16 v[30:33], v[186:189], v[202:205], v[30:33]
	v_mfma_f32_16x16x32_bf16 v[74:77], v[138:141], v[232:235], v[74:77]
	v_mfma_f32_16x16x32_bf16 v[114:117], v[186:189], v[232:235], v[114:117]
	v_mfma_f32_16x16x32_bf16 v[18:21], v[138:141], v[240:243], v[18:21]
	v_mfma_f32_16x16x32_bf16 v[22:25], v[186:189], v[240:243], v[22:25]
	s_setprio 0
	s_barrier
	ds_read_b128 v[118:121], v146
	ds_read_b128 v[122:125], v146 offset:1024
	ds_read_b128 v[126:129], v146 offset:2048
	ds_read_b128 v[130:133], v146 offset:3072
	ds_read_b128 v[134:137], v160
	ds_read_b128 v[138:141], v160 offset:1024
	ds_read_b128 v[182:185], v160 offset:2048
	ds_read_b128 v[186:189], v160 offset:3072
	s_add_u32 s20, s20, 0x10180
	s_addc_u32 s21, s21, 0
	s_mov_b32 m0, s53
	v_lshl_add_u64 v[40:41], s[20:21], 0, v[34:35]
	ds_read_b128 v[190:193], v45
	ds_read_b128 v[194:197], v45 offset:1024
	ds_read_b128 v[198:201], v45 offset:2048
	ds_read_b128 v[202:205], v45 offset:3072
	ds_read_b128 v[206:209], v45 offset:4096
	ds_read_b128 v[232:235], v45 offset:5120
	ds_read_b128 v[236:239], v45 offset:6144
	ds_read_b128 v[240:243], v45 offset:7168
	global_load_lds_dwordx4 v[40:41], off
	v_lshl_add_u64 v[40:41], s[20:21], 0, v[36:37]
	s_mov_b32 m0, s11
	s_nop 0
	global_load_lds_dwordx4 v[40:41], off
	s_waitcnt vmcnt(8)
	s_waitcnt lgkmcnt(0)
	s_barrier
	s_setprio 1
	s_waitcnt lgkmcnt(0)
	v_mfma_f32_16x16x32_bf16 v[78:81], v[118:121], v[190:193], v[78:81]
	v_mfma_f32_16x16x32_bf16 v[82:85], v[126:129], v[190:193], v[82:85]
	v_mfma_f32_16x16x32_bf16 v[86:89], v[118:121], v[198:201], v[86:89]
	v_mfma_f32_16x16x32_bf16 v[90:93], v[126:129], v[198:201], v[90:93]
	v_mfma_f32_16x16x32_bf16 v[94:97], v[118:121], v[206:209], v[94:97]
	v_mfma_f32_16x16x32_bf16 v[98:101], v[126:129], v[206:209], v[98:101]
	v_mfma_f32_16x16x32_bf16 v[102:105], v[118:121], v[236:239], v[102:105]
	v_mfma_f32_16x16x32_bf16 v[106:109], v[126:129], v[236:239], v[106:109]
	v_mfma_f32_16x16x32_bf16 v[78:81], v[122:125], v[194:197], v[78:81]
	v_mfma_f32_16x16x32_bf16 v[82:85], v[130:133], v[194:197], v[82:85]
	v_mfma_f32_16x16x32_bf16 v[86:89], v[122:125], v[202:205], v[86:89]
	v_mfma_f32_16x16x32_bf16 v[90:93], v[130:133], v[202:205], v[90:93]
	v_mfma_f32_16x16x32_bf16 v[94:97], v[122:125], v[232:235], v[94:97]
	v_mfma_f32_16x16x32_bf16 v[98:101], v[130:133], v[232:235], v[98:101]
	v_mfma_f32_16x16x32_bf16 v[102:105], v[122:125], v[240:243], v[102:105]
	v_mfma_f32_16x16x32_bf16 v[106:109], v[130:133], v[240:243], v[106:109]
	v_mfma_f32_16x16x32_bf16 v[110:113], v[134:137], v[190:193], v[110:113]
	v_mfma_f32_16x16x32_bf16 v[46:49], v[182:185], v[190:193], v[46:49]
	v_mfma_f32_16x16x32_bf16 v[50:53], v[134:137], v[198:201], v[50:53]
	v_mfma_f32_16x16x32_bf16 v[54:57], v[182:185], v[198:201], v[54:57]
	v_mfma_f32_16x16x32_bf16 v[58:61], v[134:137], v[206:209], v[58:61]
	v_mfma_f32_16x16x32_bf16 v[62:65], v[182:185], v[206:209], v[62:65]
	v_mfma_f32_16x16x32_bf16 v[66:69], v[134:137], v[236:239], v[66:69]
	v_mfma_f32_16x16x32_bf16 v[70:73], v[182:185], v[236:239], v[70:73]
	v_mfma_f32_16x16x32_bf16 v[110:113], v[138:141], v[194:197], v[110:113]
	v_mfma_f32_16x16x32_bf16 v[46:49], v[186:189], v[194:197], v[46:49]
	v_mfma_f32_16x16x32_bf16 v[50:53], v[138:141], v[202:205], v[50:53]
	v_mfma_f32_16x16x32_bf16 v[54:57], v[186:189], v[202:205], v[54:57]
	v_mfma_f32_16x16x32_bf16 v[58:61], v[138:141], v[232:235], v[58:61]
	v_mfma_f32_16x16x32_bf16 v[62:65], v[186:189], v[232:235], v[62:65]
	v_mfma_f32_16x16x32_bf16 v[66:69], v[138:141], v[240:243], v[66:69]
	v_mfma_f32_16x16x32_bf16 v[70:73], v[186:189], v[240:243], v[70:73]
	s_setprio 0
	s_barrier
	s_mov_b32 m0, s47
	v_lshl_add_u64 v[40:41], s[24:25], 0, v[0:1]
	s_add_u32 s20, s24, 0x10000
	ds_read_b128 v[190:193], v45 offset:16384
	ds_read_b128 v[194:197], v45 offset:17408
	ds_read_b128 v[198:201], v45 offset:18432
	ds_read_b128 v[202:205], v45 offset:19456
	ds_read_b128 v[206:209], v45 offset:20480
	ds_read_b128 v[232:235], v45 offset:21504
	ds_read_b128 v[236:239], v45 offset:22528
	ds_read_b128 v[240:243], v45 offset:23552
	global_load_lds_dwordx4 v[40:41], off
	v_lshl_add_u64 v[210:211], s[24:25], 0, v[38:39]
	s_mov_b32 m0, s13
	s_addc_u32 s21, s25, 0
	global_load_lds_dwordx4 v[210:211], off
	v_lshl_add_u64 v[220:221], s[20:21], 0, v[0:1]
	s_mov_b32 m0, s45
	v_lshl_add_u64 v[222:223], s[26:27], 0, v[36:37]
	global_load_lds_dwordx4 v[220:221], off
	v_lshl_add_u64 v[220:221], s[20:21], 0, v[38:39]
	s_mov_b32 m0, s46
	s_nop 0
	global_load_lds_dwordx4 v[220:221], off
	v_lshl_add_u64 v[220:221], s[26:27], 0, v[34:35]
	s_mov_b32 m0, s15
	s_nop 0
	global_load_lds_dwordx4 v[220:221], off
	s_mov_b32 m0, s37
	s_nop 0
	global_load_lds_dwordx4 v[222:223], off
	s_waitcnt vmcnt(8)
	s_waitcnt lgkmcnt(0)
	s_barrier
	s_setprio 1
	s_waitcnt lgkmcnt(0)
	v_mfma_f32_16x16x32_bf16 v[142:145], v[118:121], v[190:193], v[142:145]
	v_mfma_f32_16x16x32_bf16 v[162:165], v[126:129], v[190:193], v[162:165]
	v_mfma_f32_16x16x32_bf16 v[166:169], v[118:121], v[198:201], v[166:169]
	v_mfma_f32_16x16x32_bf16 v[170:173], v[126:129], v[198:201], v[170:173]
	v_mfma_f32_16x16x32_bf16 v[174:177], v[118:121], v[206:209], v[174:177]
	v_mfma_f32_16x16x32_bf16 v[178:181], v[126:129], v[206:209], v[178:181]
	v_mfma_f32_16x16x32_bf16 v[2:5], v[118:121], v[236:239], v[2:5]
	v_mfma_f32_16x16x32_bf16 v[6:9], v[126:129], v[236:239], v[6:9]
	v_mfma_f32_16x16x32_bf16 v[142:145], v[122:125], v[194:197], v[142:145]
	v_mfma_f32_16x16x32_bf16 v[162:165], v[130:133], v[194:197], v[162:165]
	v_mfma_f32_16x16x32_bf16 v[166:169], v[122:125], v[202:205], v[166:169]
	v_mfma_f32_16x16x32_bf16 v[170:173], v[130:133], v[202:205], v[170:173]
	v_mfma_f32_16x16x32_bf16 v[174:177], v[122:125], v[232:235], v[174:177]
	v_mfma_f32_16x16x32_bf16 v[178:181], v[130:133], v[232:235], v[178:181]
	v_mfma_f32_16x16x32_bf16 v[2:5], v[122:125], v[240:243], v[2:5]
	v_mfma_f32_16x16x32_bf16 v[6:9], v[130:133], v[240:243], v[6:9]
	v_mfma_f32_16x16x32_bf16 v[14:17], v[182:185], v[190:193], v[14:17]
	v_mfma_f32_16x16x32_bf16 v[118:121], v[186:189], v[194:197], v[14:17]
	v_mfma_f32_16x16x32_bf16 v[14:17], v[134:137], v[198:201], v[26:29]
	v_mfma_f32_16x16x32_bf16 v[26:29], v[138:141], v[202:205], v[14:17]
	v_mfma_f32_16x16x32_bf16 v[14:17], v[182:185], v[198:201], v[30:33]
	v_mfma_f32_16x16x32_bf16 v[122:125], v[186:189], v[202:205], v[14:17]
	v_mfma_f32_16x16x32_bf16 v[14:17], v[134:137], v[206:209], v[74:77]
	v_mfma_f32_16x16x32_bf16 v[74:77], v[138:141], v[232:235], v[14:17]
	v_mfma_f32_16x16x32_bf16 v[14:17], v[182:185], v[206:209], v[114:117]
	v_mfma_f32_16x16x32_bf16 v[114:117], v[186:189], v[232:235], v[14:17]
	v_mfma_f32_16x16x32_bf16 v[14:17], v[134:137], v[236:239], v[18:21]
	v_mfma_f32_16x16x32_bf16 v[10:13], v[134:137], v[190:193], v[10:13]
	v_mfma_f32_16x16x32_bf16 v[126:129], v[138:141], v[240:243], v[14:17]
	v_mfma_f32_16x16x32_bf16 v[14:17], v[182:185], v[236:239], v[22:25]
	v_mfma_f32_16x16x32_bf16 v[10:13], v[138:141], v[194:197], v[10:13]
	v_mfma_f32_16x16x32_bf16 v[130:133], v[186:189], v[240:243], v[14:17]
	s_setprio 0
	s_barrier
	s_nop 3
	ds_read_b128 v[14:17], v231
	ds_read_b128 v[18:21], v231 offset:1024
	ds_read_b128 v[134:137], v231 offset:2048
	ds_read_b128 v[138:141], v231 offset:3072
	ds_read_b128 v[182:185], v246
	ds_read_b128 v[186:189], v246 offset:1024
	ds_read_b128 v[190:193], v246 offset:2048
	ds_read_b128 v[194:197], v246 offset:3072
	s_add_u32 s20, s26, 0x10000
	s_addc_u32 s21, s27, 0
	s_mov_b32 m0, s38
	v_lshl_add_u64 v[244:245], s[20:21], 0, v[34:35]
	ds_read_b128 v[22:25], v45 offset:32768
	ds_read_b128 v[30:33], v45 offset:33792
	ds_read_b128 v[198:201], v45 offset:34816
	ds_read_b128 v[202:205], v45 offset:35840
	ds_read_b128 v[206:209], v45 offset:36864
	ds_read_b128 v[232:235], v45 offset:37888
	ds_read_b128 v[236:239], v45 offset:38912
	ds_read_b128 v[240:243], v45 offset:39936
	global_load_lds_dwordx4 v[244:245], off
	v_lshl_add_u64 v[244:245], s[20:21], 0, v[36:37]
	s_mov_b32 m0, s39
	s_nop 0
	global_load_lds_dwordx4 v[244:245], off
	s_waitcnt vmcnt(8)
	s_waitcnt lgkmcnt(0)
	s_barrier
	s_setprio 1
	s_waitcnt lgkmcnt(0)
	v_mfma_f32_16x16x32_bf16 v[78:81], v[14:17], v[22:25], v[78:81]
	v_mfma_f32_16x16x32_bf16 v[82:85], v[134:137], v[22:25], v[82:85]
	v_mfma_f32_16x16x32_bf16 v[86:89], v[14:17], v[198:201], v[86:89]
	v_mfma_f32_16x16x32_bf16 v[90:93], v[134:137], v[198:201], v[90:93]
	v_mfma_f32_16x16x32_bf16 v[94:97], v[14:17], v[206:209], v[94:97]
	v_mfma_f32_16x16x32_bf16 v[98:101], v[134:137], v[206:209], v[98:101]
	v_mfma_f32_16x16x32_bf16 v[102:105], v[14:17], v[236:239], v[102:105]
	v_mfma_f32_16x16x32_bf16 v[106:109], v[134:137], v[236:239], v[106:109]
	v_mfma_f32_16x16x32_bf16 v[78:81], v[18:21], v[30:33], v[78:81]
	v_mfma_f32_16x16x32_bf16 v[82:85], v[138:141], v[30:33], v[82:85]
	v_mfma_f32_16x16x32_bf16 v[86:89], v[18:21], v[202:205], v[86:89]
	v_mfma_f32_16x16x32_bf16 v[90:93], v[138:141], v[202:205], v[90:93]
	v_mfma_f32_16x16x32_bf16 v[94:97], v[18:21], v[232:235], v[94:97]
	v_mfma_f32_16x16x32_bf16 v[98:101], v[138:141], v[232:235], v[98:101]
	v_mfma_f32_16x16x32_bf16 v[102:105], v[18:21], v[240:243], v[102:105]
	v_mfma_f32_16x16x32_bf16 v[106:109], v[138:141], v[240:243], v[106:109]
	v_mfma_f32_16x16x32_bf16 v[110:113], v[182:185], v[22:25], v[110:113]
	v_mfma_f32_16x16x32_bf16 v[22:25], v[190:193], v[22:25], v[46:49]
	v_mfma_f32_16x16x32_bf16 v[46:49], v[194:197], v[30:33], v[22:25]
	v_mfma_f32_16x16x32_bf16 v[22:25], v[182:185], v[198:201], v[50:53]
	v_mfma_f32_16x16x32_bf16 v[50:53], v[186:189], v[202:205], v[22:25]
	v_mfma_f32_16x16x32_bf16 v[22:25], v[190:193], v[198:201], v[54:57]
	v_mfma_f32_16x16x32_bf16 v[54:57], v[194:197], v[202:205], v[22:25]
	v_mfma_f32_16x16x32_bf16 v[22:25], v[182:185], v[206:209], v[58:61]
	v_mfma_f32_16x16x32_bf16 v[58:61], v[186:189], v[232:235], v[22:25]
	v_mfma_f32_16x16x32_bf16 v[22:25], v[190:193], v[206:209], v[62:65]
	v_mfma_f32_16x16x32_bf16 v[62:65], v[194:197], v[232:235], v[22:25]
	v_mfma_f32_16x16x32_bf16 v[22:25], v[182:185], v[236:239], v[66:69]
	v_mfma_f32_16x16x32_bf16 v[66:69], v[186:189], v[240:243], v[22:25]
	v_mfma_f32_16x16x32_bf16 v[22:25], v[190:193], v[236:239], v[70:73]
	v_mfma_f32_16x16x32_bf16 v[110:113], v[186:189], v[30:33], v[110:113]
	v_mfma_f32_16x16x32_bf16 v[70:73], v[194:197], v[240:243], v[22:25]
	s_setprio 0
	s_barrier
	s_mov_b32 m0, s54
	s_nop 2
	v_lshl_add_u64 v[22:23], v[40:41], 0, s[90:91]
	s_add_u32 s20, s24, 0x10080
	ds_read_b128 v[198:201], v45 offset:49152
	ds_read_b128 v[202:205], v45 offset:50176
	ds_read_b128 v[206:209], v45 offset:51200
	ds_read_b128 v[232:235], v45 offset:52224
	ds_read_b128 v[236:239], v45 offset:53248
	ds_read_b128 v[240:243], v45 offset:54272
	ds_read_b128 v[244:247], v45 offset:55296
	ds_read_b128 v[248:251], v45 offset:56320
	global_load_lds_dwordx4 v[22:23], off
	v_lshl_add_u64 v[22:23], v[210:211], 0, s[90:91]
	s_mov_b32 m0, s52
	s_addc_u32 s21, s25, 0
	global_load_lds_dwordx4 v[22:23], off
	v_lshl_add_u64 v[22:23], s[20:21], 0, v[0:1]
	s_mov_b32 m0, s22
	s_nop 0
	global_load_lds_dwordx4 v[22:23], off
	v_lshl_add_u64 v[22:23], s[20:21], 0, v[38:39]
	s_mov_b32 m0, s23
	s_nop 0
	global_load_lds_dwordx4 v[22:23], off
	v_lshl_add_u64 v[22:23], v[220:221], 0, s[90:91]
	s_mov_b32 m0, s40
	s_nop 0
	global_load_lds_dwordx4 v[22:23], off
	v_lshl_add_u64 v[22:23], v[222:223], 0, s[90:91]
	s_mov_b32 m0, s41
	s_nop 0
	global_load_lds_dwordx4 v[22:23], off
	s_waitcnt vmcnt(8)
	s_waitcnt lgkmcnt(0)
	s_barrier
	s_setprio 1
	s_waitcnt lgkmcnt(0)
	v_mfma_f32_16x16x32_bf16 v[22:25], v[14:17], v[198:201], v[142:145]
	v_mfma_f32_16x16x32_bf16 v[142:145], v[18:21], v[202:205], v[22:25]
	v_mfma_f32_16x16x32_bf16 v[22:25], v[134:137], v[198:201], v[162:165]
	v_mfma_f32_16x16x32_bf16 v[162:165], v[138:141], v[202:205], v[22:25]
	v_mfma_f32_16x16x32_bf16 v[22:25], v[14:17], v[206:209], v[166:169]
	v_mfma_f32_16x16x32_bf16 v[166:169], v[18:21], v[232:235], v[22:25]
	v_mfma_f32_16x16x32_bf16 v[22:25], v[134:137], v[206:209], v[170:173]
	v_mfma_f32_16x16x32_bf16 v[170:173], v[138:141], v[232:235], v[22:25]
	v_mfma_f32_16x16x32_bf16 v[22:25], v[14:17], v[236:239], v[174:177]
	v_mfma_f32_16x16x32_bf16 v[2:5], v[14:17], v[244:247], v[2:5]
	v_mfma_f32_16x16x32_bf16 v[30:33], v[18:21], v[240:243], v[22:25]
	v_mfma_f32_16x16x32_bf16 v[22:25], v[134:137], v[236:239], v[178:181]
	v_mfma_f32_16x16x32_bf16 v[14:17], v[18:21], v[248:251], v[2:5]
	v_mfma_f32_16x16x32_bf16 v[2:5], v[134:137], v[244:247], v[6:9]
	v_mfma_f32_16x16x32_bf16 v[22:25], v[138:141], v[240:243], v[22:25]
	v_mfma_f32_16x16x32_bf16 v[6:9], v[138:141], v[248:251], v[2:5]
	v_mfma_f32_16x16x32_bf16 v[2:5], v[182:185], v[198:201], v[10:13]
	v_mfma_f32_16x16x32_bf16 v[134:137], v[186:189], v[202:205], v[2:5]
	v_mfma_f32_16x16x32_bf16 v[2:5], v[190:193], v[198:201], v[118:121]
	v_mfma_f32_16x16x32_bf16 v[118:121], v[194:197], v[202:205], v[2:5]
	v_mfma_f32_16x16x32_bf16 v[2:5], v[182:185], v[206:209], v[26:29]
	v_mfma_f32_16x16x32_bf16 v[138:141], v[186:189], v[232:235], v[2:5]
	v_mfma_f32_16x16x32_bf16 v[2:5], v[190:193], v[206:209], v[122:125]
	v_mfma_f32_16x16x32_bf16 v[122:125], v[194:197], v[232:235], v[2:5]
	v_mfma_f32_16x16x32_bf16 v[2:5], v[182:185], v[236:239], v[74:77]
	v_mfma_f32_16x16x32_bf16 v[26:29], v[186:189], v[240:243], v[2:5]
	v_mfma_f32_16x16x32_bf16 v[2:5], v[190:193], v[236:239], v[114:117]
	v_mfma_f32_16x16x32_bf16 v[18:21], v[194:197], v[240:243], v[2:5]
	v_mfma_f32_16x16x32_bf16 v[2:5], v[182:185], v[244:247], v[126:129]
	v_mfma_f32_16x16x32_bf16 v[10:13], v[186:189], v[248:251], v[2:5]
	v_mfma_f32_16x16x32_bf16 v[2:5], v[190:193], v[244:247], v[130:133]
	v_mfma_f32_16x16x32_bf16 v[2:5], v[194:197], v[248:251], v[2:5]
	s_setprio 0
	s_barrier
	v_lshl_add_u32 v114, s14, 8, v42
	v_lshl_or_b32 v40, s44, 8, v44
	v_ashrrev_i32_e32 v41, 31, v40
	v_ashrrev_i32_e32 v115, 31, v114
	v_lshl_add_u64 v[116:117], v[40:41], 1, s[8:9]
	v_lshlrev_b64 v[40:41], 16, v[114:115]
	v_lshl_add_u64 v[40:41], v[116:117], 0, v[40:41]
	v_cvt_pk_bf16_f32 v74, v78, v79
	v_cvt_pk_bf16_f32 v75, v80, v81
	v_cvt_pk_bf16_f32 v76, v82, v83
	v_cvt_pk_bf16_f32 v77, v84, v85
	global_store_dwordx4 v[40:41], v[74:77], off
	s_mov_b64 s[20:21], 0x800000
	s_mov_b32 s11, 0x900000
	v_cvt_pk_bf16_f32 v74, v110, v111
	v_cvt_pk_bf16_f32 v75, v112, v113
	v_cvt_pk_bf16_f32 v76, v46, v47
	v_or_b32_e32 v46, 16, v114
	v_ashrrev_i32_e32 v47, 31, v46
	v_lshlrev_b64 v[46:47], 16, v[46:47]
	v_cvt_pk_bf16_f32 v77, v48, v49
	global_store_dwordx4 v[40:41], v[74:77], off offset:256
	s_add_i32 s43, s43, s28
	s_mov_b32 s44, s10
	v_lshl_add_u64 v[74:75], v[116:117], 0, v[46:47]
	v_cvt_pk_bf16_f32 v46, v86, v87
	v_cvt_pk_bf16_f32 v47, v88, v89
	v_cvt_pk_bf16_f32 v48, v90, v91
	v_cvt_pk_bf16_f32 v49, v92, v93
	global_store_dwordx4 v[74:75], v[46:49], off
	s_mov_b32 s14, s12
	s_mov_b64 s[22:23], s[18:19]
	v_cvt_pk_bf16_f32 v46, v50, v51
	v_cvt_pk_bf16_f32 v47, v52, v53
	v_cvt_pk_bf16_f32 v48, v54, v55
	v_cvt_pk_bf16_f32 v49, v56, v57
	global_store_dwordx4 v[74:75], v[46:49], off offset:256
	v_add_co_u32_e32 v52, vcc, s89, v40
	s_nop 0
	v_or_b32_e32 v46, 32, v114
	v_ashrrev_i32_e32 v47, 31, v46
	v_lshlrev_b64 v[46:47], 16, v[46:47]
	v_lshl_add_u64 v[50:51], v[116:117], 0, v[46:47]
	v_cvt_pk_bf16_f32 v46, v94, v95
	v_cvt_pk_bf16_f32 v47, v96, v97
	v_cvt_pk_bf16_f32 v48, v98, v99
	v_cvt_pk_bf16_f32 v49, v100, v101
	global_store_dwordx4 v[50:51], v[46:49], off
	v_addc_co_u32_e32 v53, vcc, 0, v41, vcc
	s_nop 0
	v_cvt_pk_bf16_f32 v46, v58, v59
	v_cvt_pk_bf16_f32 v47, v60, v61
	v_cvt_pk_bf16_f32 v48, v62, v63
	v_cvt_pk_bf16_f32 v49, v64, v65
	global_store_dwordx4 v[50:51], v[46:49], off offset:256
	s_nop 1
	v_or_b32_e32 v46, 48, v114
	v_ashrrev_i32_e32 v47, 31, v46
	v_lshlrev_b64 v[46:47], 16, v[46:47]
	v_lshl_add_u64 v[50:51], v[116:117], 0, v[46:47]
	v_cvt_pk_bf16_f32 v46, v102, v103
	v_cvt_pk_bf16_f32 v47, v104, v105
	v_cvt_pk_bf16_f32 v48, v106, v107
	v_cvt_pk_bf16_f32 v49, v108, v109
	global_store_dwordx4 v[50:51], v[46:49], off
	s_nop 1
	v_cvt_pk_bf16_f32 v46, v66, v67
	v_cvt_pk_bf16_f32 v47, v68, v69
	v_cvt_pk_bf16_f32 v48, v70, v71
	v_cvt_pk_bf16_f32 v49, v72, v73
	global_store_dwordx4 v[50:51], v[46:49], off offset:256
	v_lshl_add_u64 v[50:51], v[40:41], 0, s[20:21]
	s_mov_b64 s[20:21], 0x900000
	v_cvt_pk_bf16_f32 v46, v142, v143
	v_cvt_pk_bf16_f32 v47, v144, v145
	v_cvt_pk_bf16_f32 v48, v162, v163
	v_cvt_pk_bf16_f32 v49, v164, v165
	global_store_dwordx4 v[52:53], v[46:49], off
	v_add_co_u32_e32 v52, vcc, s11, v40
	s_nop 0
	v_cvt_pk_bf16_f32 v46, v134, v135
	v_cvt_pk_bf16_f32 v47, v136, v137
	v_cvt_pk_bf16_f32 v48, v118, v119
	v_cvt_pk_bf16_f32 v49, v120, v121
	global_store_dwordx4 v[50:51], v[46:49], off offset:256
	v_lshl_add_u64 v[50:51], v[40:41], 0, s[20:21]
	v_addc_co_u32_e32 v53, vcc, 0, v41, vcc
	v_cvt_pk_bf16_f32 v46, v166, v167
	v_cvt_pk_bf16_f32 v47, v168, v169
	v_cvt_pk_bf16_f32 v48, v170, v171
	v_cvt_pk_bf16_f32 v49, v172, v173
	s_mov_b32 s11, 0xa00000
	global_store_dwordx4 v[52:53], v[46:49], off
	s_mov_b64 s[20:21], 0xa00000
	s_nop 0
	v_cvt_pk_bf16_f32 v46, v138, v139
	v_cvt_pk_bf16_f32 v47, v140, v141
	v_cvt_pk_bf16_f32 v48, v122, v123
	v_cvt_pk_bf16_f32 v49, v124, v125
	global_store_dwordx4 v[50:51], v[46:49], off offset:256
	v_cvt_pk_bf16_f32 v30, v30, v31
	v_cvt_pk_bf16_f32 v31, v32, v33
	v_cvt_pk_bf16_f32 v32, v22, v23
	v_add_co_u32_e32 v22, vcc, s11, v40
	s_nop 0
	v_lshl_add_u64 v[46:47], v[40:41], 0, s[20:21]
	v_addc_co_u32_e32 v23, vcc, 0, v41, vcc
	s_mov_b32 s11, 0xb00000
	v_cvt_pk_bf16_f32 v33, v24, v25
	global_store_dwordx4 v[22:23], v[30:33], off
	v_cvt_pk_bf16_f32 v22, v26, v27
	v_cvt_pk_bf16_f32 v23, v28, v29
	v_cvt_pk_bf16_f32 v24, v18, v19
	v_cvt_pk_bf16_f32 v25, v20, v21
	global_store_dwordx4 v[46:47], v[22:25], off offset:256
	v_cvt_pk_bf16_f32 v14, v14, v15
	v_cvt_pk_bf16_f32 v15, v16, v17
	v_cvt_pk_bf16_f32 v16, v6, v7
	v_add_co_u32_e32 v6, vcc, s11, v40
	s_mov_b64 s[20:21], 0xb00000
	s_nop 0
	v_addc_co_u32_e32 v7, vcc, 0, v41, vcc
	v_lshl_add_u64 v[18:19], v[40:41], 0, s[20:21]
	s_andn2_b64 vcc, exec, s[4:5]
	s_mov_b64 s[20:21], s[16:17]
	v_cvt_pk_bf16_f32 v17, v8, v9
	global_store_dwordx4 v[6:7], v[14:17], off
	v_cvt_pk_bf16_f32 v6, v10, v11
	v_cvt_pk_bf16_f32 v7, v12, v13
	v_cvt_pk_bf16_f32 v8, v2, v3
	v_cvt_pk_bf16_f32 v9, v4, v5
	global_store_dwordx4 v[18:19], v[6:9], off offset:256
	s_cbranch_vccz .LBB0_592

.LBB0_1217:
	s_add_u32 s22, s20, 0x100
	s_addc_u32 s23, s21, 0
	s_add_i32 s55, 0, 0x10000
	s_cmp_eq_u32 s54, 12
	s_cselect_b32 s27, s13, s23
	s_cselect_b32 s26, s46, s22
	v_add_u32_e32 v140, s55, v143
	s_cselect_b32 s25, s11, s53
	s_cselect_b32 s24, s47, s52
	s_add_i32 s56, 0, 0x14000
	ds_read_b128 v[136:139], v140
	ds_read_b128 v[162:165], v140 offset:1024
	ds_read_b128 v[166:169], v140 offset:2048
	ds_read_b128 v[170:173], v140 offset:3072
	v_add_u32_e32 v140, s56, v143
	ds_read_b128 v[174:177], v140
	ds_read_b128 v[178:181], v140 offset:1024
	ds_read_b128 v[182:185], v140 offset:2048
	ds_read_b128 v[186:189], v140 offset:3072
	v_lshl_add_u64 v[140:141], s[20:21], 0, v[132:133]
	s_add_i32 m0, s38, 0xc000
	ds_read_b128 v[190:193], v145
	ds_read_b128 v[194:197], v145 offset:1024
	ds_read_b128 v[198:201], v145 offset:2048
	ds_read_b128 v[202:205], v145 offset:3072
	ds_read_b128 v[206:209], v145 offset:4096
	ds_read_b128 v[220:223], v145 offset:5120
	ds_read_b128 v[232:235], v145 offset:6144
	ds_read_b128 v[236:239], v145 offset:7168
	global_load_lds_dwordx4 v[140:141], off
	v_lshl_add_u64 v[140:141], s[20:21], 0, v[134:135]
	s_add_i32 m0, s38, 0xe000
	s_nop 0
	global_load_lds_dwordx4 v[140:141], off
	s_waitcnt vmcnt(8)
	s_waitcnt lgkmcnt(0)
	s_barrier
	s_setprio 1
	s_waitcnt lgkmcnt(0)
	v_mfma_f32_16x16x32_bf16 v[126:129], v[136:139], v[190:193], v[126:129]
	v_mfma_f32_16x16x32_bf16 v[122:125], v[166:169], v[190:193], v[122:125]
	v_mfma_f32_16x16x32_bf16 v[110:113], v[136:139], v[198:201], v[110:113]
	v_mfma_f32_16x16x32_bf16 v[106:109], v[166:169], v[198:201], v[106:109]
	v_mfma_f32_16x16x32_bf16 v[94:97], v[136:139], v[206:209], v[94:97]
	v_mfma_f32_16x16x32_bf16 v[90:93], v[166:169], v[206:209], v[90:93]
	v_mfma_f32_16x16x32_bf16 v[78:81], v[136:139], v[232:235], v[78:81]
	v_mfma_f32_16x16x32_bf16 v[74:77], v[166:169], v[232:235], v[74:77]
	v_mfma_f32_16x16x32_bf16 v[126:129], v[162:165], v[194:197], v[126:129]
	v_mfma_f32_16x16x32_bf16 v[122:125], v[170:173], v[194:197], v[122:125]
	v_mfma_f32_16x16x32_bf16 v[110:113], v[162:165], v[202:205], v[110:113]
	v_mfma_f32_16x16x32_bf16 v[106:109], v[170:173], v[202:205], v[106:109]
	v_mfma_f32_16x16x32_bf16 v[94:97], v[162:165], v[220:223], v[94:97]
	v_mfma_f32_16x16x32_bf16 v[90:93], v[170:173], v[220:223], v[90:93]
	v_mfma_f32_16x16x32_bf16 v[78:81], v[162:165], v[236:239], v[78:81]
	v_mfma_f32_16x16x32_bf16 v[74:77], v[170:173], v[236:239], v[74:77]
	v_mfma_f32_16x16x32_bf16 v[118:121], v[174:177], v[190:193], v[118:121]
	v_mfma_f32_16x16x32_bf16 v[114:117], v[182:185], v[190:193], v[114:117]
	v_mfma_f32_16x16x32_bf16 v[102:105], v[174:177], v[198:201], v[102:105]
	v_mfma_f32_16x16x32_bf16 v[98:101], v[182:185], v[198:201], v[98:101]
	v_mfma_f32_16x16x32_bf16 v[86:89], v[174:177], v[206:209], v[86:89]
	v_mfma_f32_16x16x32_bf16 v[82:85], v[182:185], v[206:209], v[82:85]
	v_mfma_f32_16x16x32_bf16 v[70:73], v[174:177], v[232:235], v[70:73]
	v_mfma_f32_16x16x32_bf16 v[66:69], v[182:185], v[232:235], v[66:69]
	v_mfma_f32_16x16x32_bf16 v[118:121], v[178:181], v[194:197], v[118:121]
	v_mfma_f32_16x16x32_bf16 v[114:117], v[186:189], v[194:197], v[114:117]
	v_mfma_f32_16x16x32_bf16 v[102:105], v[178:181], v[202:205], v[102:105]
	v_mfma_f32_16x16x32_bf16 v[98:101], v[186:189], v[202:205], v[98:101]
	v_mfma_f32_16x16x32_bf16 v[86:89], v[178:181], v[220:223], v[86:89]
	v_mfma_f32_16x16x32_bf16 v[82:85], v[186:189], v[220:223], v[82:85]
	v_mfma_f32_16x16x32_bf16 v[70:73], v[178:181], v[236:239], v[70:73]
	v_mfma_f32_16x16x32_bf16 v[66:69], v[186:189], v[236:239], v[66:69]
	s_setprio 0
	s_barrier
	s_add_i32 s20, s55, s37
	v_lshl_add_u64 v[140:141], s[24:25], 0, v[0:1]
	s_mov_b32 m0, s20
	ds_read_b128 v[190:193], v145 offset:16384
	ds_read_b128 v[194:197], v145 offset:17408
	ds_read_b128 v[198:201], v145 offset:18432
	ds_read_b128 v[202:205], v145 offset:19456
	ds_read_b128 v[206:209], v145 offset:20480
	ds_read_b128 v[220:223], v145 offset:21504
	ds_read_b128 v[232:235], v145 offset:22528
	ds_read_b128 v[236:239], v145 offset:23552
	global_load_lds_dwordx4 v[140:141], off
	s_add_i32 m0, s20, 0x2000
	s_add_u32 s20, s24, 0x40000
	v_lshl_add_u64 v[210:211], s[24:25], 0, v[130:131]
	s_addc_u32 s21, s25, 0
	s_add_i32 s55, s56, s37
	global_load_lds_dwordx4 v[210:211], off
	v_lshl_add_u64 v[240:241], s[20:21], 0, v[0:1]
	s_mov_b32 m0, s55
	v_lshl_add_u64 v[242:243], s[26:27], 0, v[130:131]
	global_load_lds_dwordx4 v[240:241], off
	v_lshl_add_u64 v[240:241], s[20:21], 0, v[130:131]
	s_add_i32 m0, s55, 0x2000
	s_nop 0
	global_load_lds_dwordx4 v[240:241], off
	v_lshl_add_u64 v[240:241], s[26:27], 0, v[0:1]
	s_mov_b32 m0, s38
	s_nop 0
	global_load_lds_dwordx4 v[240:241], off
	s_mov_b32 m0, s39
	s_nop 0
	global_load_lds_dwordx4 v[242:243], off
	s_waitcnt vmcnt(8)
	s_waitcnt lgkmcnt(0)
	s_barrier
	s_setprio 1
	s_waitcnt lgkmcnt(0)
	v_mfma_f32_16x16x32_bf16 v[62:65], v[136:139], v[190:193], v[62:65]
	v_mfma_f32_16x16x32_bf16 v[58:61], v[166:169], v[190:193], v[58:61]
	v_mfma_f32_16x16x32_bf16 v[46:49], v[136:139], v[198:201], v[46:49]
	v_mfma_f32_16x16x32_bf16 v[42:45], v[166:169], v[198:201], v[42:45]
	v_mfma_f32_16x16x32_bf16 v[30:33], v[136:139], v[206:209], v[30:33]
	v_mfma_f32_16x16x32_bf16 v[26:29], v[166:169], v[206:209], v[26:29]
	v_mfma_f32_16x16x32_bf16 v[14:17], v[136:139], v[232:235], v[14:17]
	v_mfma_f32_16x16x32_bf16 v[10:13], v[166:169], v[232:235], v[10:13]
	v_mfma_f32_16x16x32_bf16 v[62:65], v[162:165], v[194:197], v[62:65]
	v_mfma_f32_16x16x32_bf16 v[58:61], v[170:173], v[194:197], v[58:61]
	v_mfma_f32_16x16x32_bf16 v[46:49], v[162:165], v[202:205], v[46:49]
	v_mfma_f32_16x16x32_bf16 v[42:45], v[170:173], v[202:205], v[42:45]
	v_mfma_f32_16x16x32_bf16 v[30:33], v[162:165], v[220:223], v[30:33]
	v_mfma_f32_16x16x32_bf16 v[26:29], v[170:173], v[220:223], v[26:29]
	v_mfma_f32_16x16x32_bf16 v[14:17], v[162:165], v[236:239], v[14:17]
	v_mfma_f32_16x16x32_bf16 v[10:13], v[170:173], v[236:239], v[10:13]
	v_mfma_f32_16x16x32_bf16 v[54:57], v[174:177], v[190:193], v[54:57]
	v_mfma_f32_16x16x32_bf16 v[50:53], v[182:185], v[190:193], v[50:53]
	v_mfma_f32_16x16x32_bf16 v[38:41], v[174:177], v[198:201], v[38:41]
	v_mfma_f32_16x16x32_bf16 v[34:37], v[182:185], v[198:201], v[34:37]
	v_mfma_f32_16x16x32_bf16 v[22:25], v[174:177], v[206:209], v[22:25]
	v_mfma_f32_16x16x32_bf16 v[18:21], v[182:185], v[206:209], v[18:21]
	v_mfma_f32_16x16x32_bf16 v[6:9], v[174:177], v[232:235], v[6:9]
	v_mfma_f32_16x16x32_bf16 v[2:5], v[182:185], v[232:235], v[2:5]
	v_mfma_f32_16x16x32_bf16 v[54:57], v[178:181], v[194:197], v[54:57]
	v_mfma_f32_16x16x32_bf16 v[50:53], v[186:189], v[194:197], v[50:53]
	v_mfma_f32_16x16x32_bf16 v[38:41], v[178:181], v[202:205], v[38:41]
	v_mfma_f32_16x16x32_bf16 v[34:37], v[186:189], v[202:205], v[34:37]
	v_mfma_f32_16x16x32_bf16 v[22:25], v[178:181], v[220:223], v[22:25]
	v_mfma_f32_16x16x32_bf16 v[18:21], v[186:189], v[220:223], v[18:21]
	v_mfma_f32_16x16x32_bf16 v[6:9], v[178:181], v[236:239], v[6:9]
	v_mfma_f32_16x16x32_bf16 v[2:5], v[186:189], v[236:239], v[2:5]
	s_setprio 0
	s_barrier
	s_add_i32 s55, 0, 0x18000
	v_add_u32_e32 v146, s55, v143
	s_add_i32 s56, 0, 0x1c000
	ds_read_b128 v[136:139], v146
	ds_read_b128 v[162:165], v146 offset:1024
	ds_read_b128 v[166:169], v146 offset:2048
	ds_read_b128 v[170:173], v146 offset:3072
	v_add_u32_e32 v146, s56, v143
	ds_read_b128 v[174:177], v146
	ds_read_b128 v[178:181], v146 offset:1024
	ds_read_b128 v[182:185], v146 offset:2048
	ds_read_b128 v[186:189], v146 offset:3072
	s_add_u32 s20, s26, 0x40000
	s_addc_u32 s21, s27, 0
	s_mov_b32 m0, s40
	v_lshl_add_u64 v[244:245], s[20:21], 0, v[0:1]
	ds_read_b128 v[190:193], v145 offset:32768
	ds_read_b128 v[194:197], v145 offset:33792
	ds_read_b128 v[198:201], v145 offset:34816
	ds_read_b128 v[202:205], v145 offset:35840
	ds_read_b128 v[206:209], v145 offset:36864
	ds_read_b128 v[220:223], v145 offset:37888
	ds_read_b128 v[232:235], v145 offset:38912
	ds_read_b128 v[236:239], v145 offset:39936
	global_load_lds_dwordx4 v[244:245], off
	v_lshl_add_u64 v[244:245], s[20:21], 0, v[130:131]
	s_mov_b32 m0, s41
	s_nop 0
	global_load_lds_dwordx4 v[244:245], off
	s_waitcnt vmcnt(8)
	s_waitcnt lgkmcnt(0)
	s_barrier
	s_setprio 1
	s_waitcnt lgkmcnt(0)
	v_mfma_f32_16x16x32_bf16 v[126:129], v[136:139], v[190:193], v[126:129]
	v_mfma_f32_16x16x32_bf16 v[122:125], v[166:169], v[190:193], v[122:125]
	v_mfma_f32_16x16x32_bf16 v[110:113], v[136:139], v[198:201], v[110:113]
	v_mfma_f32_16x16x32_bf16 v[106:109], v[166:169], v[198:201], v[106:109]
	v_mfma_f32_16x16x32_bf16 v[94:97], v[136:139], v[206:209], v[94:97]
	v_mfma_f32_16x16x32_bf16 v[90:93], v[166:169], v[206:209], v[90:93]
	v_mfma_f32_16x16x32_bf16 v[78:81], v[136:139], v[232:235], v[78:81]
	v_mfma_f32_16x16x32_bf16 v[74:77], v[166:169], v[232:235], v[74:77]
	v_mfma_f32_16x16x32_bf16 v[126:129], v[162:165], v[194:197], v[126:129]
	v_mfma_f32_16x16x32_bf16 v[122:125], v[170:173], v[194:197], v[122:125]
	v_mfma_f32_16x16x32_bf16 v[110:113], v[162:165], v[202:205], v[110:113]
	v_mfma_f32_16x16x32_bf16 v[106:109], v[170:173], v[202:205], v[106:109]
	v_mfma_f32_16x16x32_bf16 v[94:97], v[162:165], v[220:223], v[94:97]
	v_mfma_f32_16x16x32_bf16 v[90:93], v[170:173], v[220:223], v[90:93]
	v_mfma_f32_16x16x32_bf16 v[78:81], v[162:165], v[236:239], v[78:81]
	v_mfma_f32_16x16x32_bf16 v[74:77], v[170:173], v[236:239], v[74:77]
	v_mfma_f32_16x16x32_bf16 v[118:121], v[174:177], v[190:193], v[118:121]
	v_mfma_f32_16x16x32_bf16 v[114:117], v[182:185], v[190:193], v[114:117]
	v_mfma_f32_16x16x32_bf16 v[102:105], v[174:177], v[198:201], v[102:105]
	v_mfma_f32_16x16x32_bf16 v[98:101], v[182:185], v[198:201], v[98:101]
	v_mfma_f32_16x16x32_bf16 v[86:89], v[174:177], v[206:209], v[86:89]
	v_mfma_f32_16x16x32_bf16 v[82:85], v[182:185], v[206:209], v[82:85]
	v_mfma_f32_16x16x32_bf16 v[70:73], v[174:177], v[232:235], v[70:73]
	v_mfma_f32_16x16x32_bf16 v[66:69], v[182:185], v[232:235], v[66:69]
	v_mfma_f32_16x16x32_bf16 v[118:121], v[178:181], v[194:197], v[118:121]
	v_mfma_f32_16x16x32_bf16 v[114:117], v[186:189], v[194:197], v[114:117]
	v_mfma_f32_16x16x32_bf16 v[102:105], v[178:181], v[202:205], v[102:105]
	v_mfma_f32_16x16x32_bf16 v[98:101], v[186:189], v[202:205], v[98:101]
	v_mfma_f32_16x16x32_bf16 v[86:89], v[178:181], v[220:223], v[86:89]
	v_mfma_f32_16x16x32_bf16 v[82:85], v[186:189], v[220:223], v[82:85]
	v_mfma_f32_16x16x32_bf16 v[70:73], v[178:181], v[236:239], v[70:73]
	v_mfma_f32_16x16x32_bf16 v[66:69], v[186:189], v[236:239], v[66:69]
	s_setprio 0
	s_barrier
	s_add_i32 s20, s55, s37
	v_lshl_add_u64 v[140:141], v[140:141], 0, s[90:91]
	s_mov_b32 m0, s20
	ds_read_b128 v[190:193], v145 offset:49152
	ds_read_b128 v[194:197], v145 offset:50176
	ds_read_b128 v[198:201], v145 offset:51200
	ds_read_b128 v[202:205], v145 offset:52224
	ds_read_b128 v[206:209], v145 offset:53248
	ds_read_b128 v[220:223], v145 offset:54272
	ds_read_b128 v[232:235], v145 offset:55296
	ds_read_b128 v[236:239], v145 offset:56320
	global_load_lds_dwordx4 v[140:141], off
	s_add_i32 m0, s20, 0x2000
	s_add_u32 s20, s24, 0x40080
	v_lshl_add_u64 v[140:141], v[210:211], 0, s[90:91]
	s_addc_u32 s21, s25, 0
	s_add_i32 s24, s56, s37
	global_load_lds_dwordx4 v[140:141], off
	v_lshl_add_u64 v[140:141], s[20:21], 0, v[0:1]
	s_mov_b32 m0, s24
	s_nop 0
	global_load_lds_dwordx4 v[140:141], off
	v_lshl_add_u64 v[140:141], s[20:21], 0, v[130:131]
	s_add_i32 m0, s24, 0x2000
	s_nop 0
	global_load_lds_dwordx4 v[140:141], off
	v_lshl_add_u64 v[140:141], v[240:241], 0, s[90:91]
	s_mov_b32 m0, s42
	s_nop 0
	global_load_lds_dwordx4 v[140:141], off
	v_lshl_add_u64 v[140:141], v[242:243], 0, s[90:91]
	s_mov_b32 m0, s43
	s_nop 0
	global_load_lds_dwordx4 v[140:141], off
	s_waitcnt vmcnt(8)
	s_waitcnt lgkmcnt(0)
	s_barrier
	s_setprio 1
	s_waitcnt lgkmcnt(0)
	v_mfma_f32_16x16x32_bf16 v[62:65], v[136:139], v[190:193], v[62:65]
	v_mfma_f32_16x16x32_bf16 v[58:61], v[166:169], v[190:193], v[58:61]
	v_mfma_f32_16x16x32_bf16 v[46:49], v[136:139], v[198:201], v[46:49]
	v_mfma_f32_16x16x32_bf16 v[42:45], v[166:169], v[198:201], v[42:45]
	v_mfma_f32_16x16x32_bf16 v[30:33], v[136:139], v[206:209], v[30:33]
	v_mfma_f32_16x16x32_bf16 v[26:29], v[166:169], v[206:209], v[26:29]
	v_mfma_f32_16x16x32_bf16 v[14:17], v[136:139], v[232:235], v[14:17]
	v_mfma_f32_16x16x32_bf16 v[10:13], v[166:169], v[232:235], v[10:13]
	v_mfma_f32_16x16x32_bf16 v[62:65], v[162:165], v[194:197], v[62:65]
	v_mfma_f32_16x16x32_bf16 v[58:61], v[170:173], v[194:197], v[58:61]
	v_mfma_f32_16x16x32_bf16 v[46:49], v[162:165], v[202:205], v[46:49]
	v_mfma_f32_16x16x32_bf16 v[42:45], v[170:173], v[202:205], v[42:45]
	v_mfma_f32_16x16x32_bf16 v[30:33], v[162:165], v[220:223], v[30:33]
	v_mfma_f32_16x16x32_bf16 v[26:29], v[170:173], v[220:223], v[26:29]
	v_mfma_f32_16x16x32_bf16 v[14:17], v[162:165], v[236:239], v[14:17]
	v_mfma_f32_16x16x32_bf16 v[10:13], v[170:173], v[236:239], v[10:13]
	v_mfma_f32_16x16x32_bf16 v[54:57], v[174:177], v[190:193], v[54:57]
	v_mfma_f32_16x16x32_bf16 v[50:53], v[182:185], v[190:193], v[50:53]
	v_mfma_f32_16x16x32_bf16 v[38:41], v[174:177], v[198:201], v[38:41]
	v_mfma_f32_16x16x32_bf16 v[34:37], v[182:185], v[198:201], v[34:37]
	v_mfma_f32_16x16x32_bf16 v[22:25], v[174:177], v[206:209], v[22:25]
	v_mfma_f32_16x16x32_bf16 v[18:21], v[182:185], v[206:209], v[18:21]
	v_mfma_f32_16x16x32_bf16 v[6:9], v[174:177], v[232:235], v[6:9]
	v_mfma_f32_16x16x32_bf16 v[2:5], v[182:185], v[232:235], v[2:5]
	v_mfma_f32_16x16x32_bf16 v[54:57], v[178:181], v[194:197], v[54:57]
	v_mfma_f32_16x16x32_bf16 v[50:53], v[186:189], v[194:197], v[50:53]
	v_mfma_f32_16x16x32_bf16 v[38:41], v[178:181], v[202:205], v[38:41]
	v_mfma_f32_16x16x32_bf16 v[34:37], v[186:189], v[202:205], v[34:37]
	v_mfma_f32_16x16x32_bf16 v[22:25], v[178:181], v[220:223], v[22:25]
	v_mfma_f32_16x16x32_bf16 v[18:21], v[186:189], v[220:223], v[18:21]
	v_mfma_f32_16x16x32_bf16 v[6:9], v[178:181], v[236:239], v[6:9]
	v_mfma_f32_16x16x32_bf16 v[2:5], v[186:189], v[236:239], v[2:5]
	s_setprio 0
	s_barrier
	s_add_i32 s54, s54, 2
	s_add_u32 s52, s52, 0x100
	s_addc_u32 s53, s53, 0
	s_cmp_gt_u32 s54, 13
	s_mov_b64 s[20:21], s[22:23]
	s_cbranch_scc0 .LBB0_1217
	s_and_b64 vcc, exec, s[8:9]
	s_cbranch_vccz .LBB0_1220
	s_barrier
